# K-loop hand-off trim: setprio 1 before opening barrier, setprio 0 after closing barrier, mid flips and redundant lgkmcnt(0) removed
# speedup vs baseline: 1.0072x; 1.0072x over previous
.LBB0_364:
	s_add_u32 s20, s18, 0xfff80080
	s_addc_u32 s21, s19, -1
	s_add_i32 s30, 0, 0x10000
	s_cmp_eq_u32 s29, 28
	s_cselect_b32 s23, s4, s21
	s_cselect_b32 s22, s24, s20
	s_cselect_b32 s21, s25, s28
	s_cselect_b32 s20, s26, s27
	s_add_i32 s42, 0, 0x14000
	v_add_u32_e32 v142, s30, v204
	v_add_u32_e32 v166, s42, v204
	ds_read_b128 v[130:133], v142
	ds_read_b128 v[134:137], v142 offset:1024
	ds_read_b128 v[138:141], v142 offset:2048
	ds_read_b128 v[142:145], v142 offset:3072
	ds_read_b128 v[146:149], v166
	ds_read_b128 v[150:153], v166 offset:1024
	ds_read_b128 v[154:157], v166 offset:2048
	ds_read_b128 v[166:169], v166 offset:3072
	v_lshl_add_u64 v[202:203], s[18:19], 0, v[162:163]
	s_add_i32 m0, s87, 0xc000
	ds_read_b128 v[170:173], v205
	ds_read_b128 v[174:177], v205 offset:1024
	ds_read_b128 v[178:181], v205 offset:2048
	ds_read_b128 v[182:185], v205 offset:3072
	ds_read_b128 v[186:189], v205 offset:4096
	ds_read_b128 v[190:193], v205 offset:5120
	ds_read_b128 v[206:209], v205 offset:6144
	ds_read_b128 v[210:213], v205 offset:7168
	global_load_lds_dwordx4 v[202:203], off
	v_lshl_add_u64 v[202:203], s[18:19], 0, v[164:165]
	s_add_i32 m0, s87, 0xe000
	s_nop 0
	global_load_lds_dwordx4 v[202:203], off
	s_waitcnt vmcnt(8)
	s_waitcnt lgkmcnt(0)
	s_setprio 1
	s_barrier
	v_mfma_f32_16x16x32_bf16 v[126:129], v[130:133], v[170:173], v[126:129]
	v_mfma_f32_16x16x32_bf16 v[122:125], v[138:141], v[170:173], v[122:125]
	v_mfma_f32_16x16x32_bf16 v[110:113], v[130:133], v[178:181], v[110:113]
	v_mfma_f32_16x16x32_bf16 v[106:109], v[138:141], v[178:181], v[106:109]
	v_mfma_f32_16x16x32_bf16 v[94:97], v[130:133], v[186:189], v[94:97]
	v_mfma_f32_16x16x32_bf16 v[90:93], v[138:141], v[186:189], v[90:93]
	v_mfma_f32_16x16x32_bf16 v[78:81], v[130:133], v[206:209], v[78:81]
	v_mfma_f32_16x16x32_bf16 v[74:77], v[138:141], v[206:209], v[74:77]
	v_mfma_f32_16x16x32_bf16 v[126:129], v[134:137], v[174:177], v[126:129]
	v_mfma_f32_16x16x32_bf16 v[122:125], v[142:145], v[174:177], v[122:125]
	v_mfma_f32_16x16x32_bf16 v[110:113], v[134:137], v[182:185], v[110:113]
	v_mfma_f32_16x16x32_bf16 v[106:109], v[142:145], v[182:185], v[106:109]
	v_mfma_f32_16x16x32_bf16 v[94:97], v[134:137], v[190:193], v[94:97]
	v_mfma_f32_16x16x32_bf16 v[90:93], v[142:145], v[190:193], v[90:93]
	v_mfma_f32_16x16x32_bf16 v[78:81], v[134:137], v[210:213], v[78:81]
	v_mfma_f32_16x16x32_bf16 v[74:77], v[142:145], v[210:213], v[74:77]
	v_mfma_f32_16x16x32_bf16 v[118:121], v[146:149], v[170:173], v[118:121]
	v_mfma_f32_16x16x32_bf16 v[114:117], v[154:157], v[170:173], v[114:117]
	v_mfma_f32_16x16x32_bf16 v[102:105], v[146:149], v[178:181], v[102:105]
	v_mfma_f32_16x16x32_bf16 v[98:101], v[154:157], v[178:181], v[98:101]
	v_mfma_f32_16x16x32_bf16 v[86:89], v[146:149], v[186:189], v[86:89]
	v_mfma_f32_16x16x32_bf16 v[82:85], v[154:157], v[186:189], v[82:85]
	v_mfma_f32_16x16x32_bf16 v[70:73], v[146:149], v[206:209], v[70:73]
	v_mfma_f32_16x16x32_bf16 v[66:69], v[154:157], v[206:209], v[66:69]
	v_mfma_f32_16x16x32_bf16 v[118:121], v[150:153], v[174:177], v[118:121]
	v_mfma_f32_16x16x32_bf16 v[114:117], v[166:169], v[174:177], v[114:117]
	v_mfma_f32_16x16x32_bf16 v[102:105], v[150:153], v[182:185], v[102:105]
	v_mfma_f32_16x16x32_bf16 v[98:101], v[166:169], v[182:185], v[98:101]
	v_mfma_f32_16x16x32_bf16 v[86:89], v[150:153], v[190:193], v[86:89]
	v_mfma_f32_16x16x32_bf16 v[82:85], v[166:169], v[190:193], v[82:85]
	v_mfma_f32_16x16x32_bf16 v[70:73], v[150:153], v[210:213], v[70:73]
	v_mfma_f32_16x16x32_bf16 v[66:69], v[166:169], v[210:213], v[66:69]
	s_barrier
	s_setprio 0
	s_add_i32 s30, s30, s39
	v_lshl_add_u64 v[202:203], s[20:21], 0, v[158:159]
	s_mov_b32 m0, s30
	ds_read_b128 v[170:173], v205 offset:16384
	ds_read_b128 v[174:177], v205 offset:17408
	ds_read_b128 v[178:181], v205 offset:18432
	ds_read_b128 v[182:185], v205 offset:19456
	ds_read_b128 v[186:189], v205 offset:20480
	ds_read_b128 v[190:193], v205 offset:21504
	ds_read_b128 v[206:209], v205 offset:22528
	ds_read_b128 v[210:213], v205 offset:23552
	global_load_lds_dwordx4 v[202:203], off
	s_add_i32 m0, s30, 0x2000
	s_add_u32 s30, s20, 0x80000
	v_lshl_add_u64 v[214:215], s[20:21], 0, v[160:161]
	s_addc_u32 s31, s21, 0
	s_add_i32 s42, s42, s39
	global_load_lds_dwordx4 v[214:215], off
	v_lshl_add_u64 v[216:217], s[30:31], 0, v[158:159]
	s_mov_b32 m0, s42
	v_lshl_add_u64 v[228:229], s[22:23], 0, v[160:161]
	global_load_lds_dwordx4 v[216:217], off
	v_lshl_add_u64 v[216:217], s[30:31], 0, v[160:161]
	s_add_i32 m0, s42, 0x2000
	s_nop 0
	global_load_lds_dwordx4 v[216:217], off
	v_lshl_add_u64 v[216:217], s[22:23], 0, v[158:159]
	s_mov_b32 m0, s87
	s_nop 0
	global_load_lds_dwordx4 v[216:217], off
	s_mov_b32 m0, s92
	s_nop 0
	global_load_lds_dwordx4 v[228:229], off
	s_waitcnt vmcnt(8)
	s_waitcnt lgkmcnt(0)
	s_setprio 1
	s_barrier
	v_mfma_f32_16x16x32_bf16 v[62:65], v[130:133], v[170:173], v[62:65]
	v_mfma_f32_16x16x32_bf16 v[58:61], v[138:141], v[170:173], v[58:61]
	v_mfma_f32_16x16x32_bf16 v[46:49], v[130:133], v[178:181], v[46:49]
	v_mfma_f32_16x16x32_bf16 v[42:45], v[138:141], v[178:181], v[42:45]
	v_mfma_f32_16x16x32_bf16 v[30:33], v[130:133], v[186:189], v[30:33]
	v_mfma_f32_16x16x32_bf16 v[26:29], v[138:141], v[186:189], v[26:29]
	v_mfma_f32_16x16x32_bf16 v[14:17], v[130:133], v[206:209], v[14:17]
	v_mfma_f32_16x16x32_bf16 v[10:13], v[138:141], v[206:209], v[10:13]
	v_mfma_f32_16x16x32_bf16 v[62:65], v[134:137], v[174:177], v[62:65]
	v_mfma_f32_16x16x32_bf16 v[58:61], v[142:145], v[174:177], v[58:61]
	v_mfma_f32_16x16x32_bf16 v[46:49], v[134:137], v[182:185], v[46:49]
	v_mfma_f32_16x16x32_bf16 v[42:45], v[142:145], v[182:185], v[42:45]
	v_mfma_f32_16x16x32_bf16 v[30:33], v[134:137], v[190:193], v[30:33]
	v_mfma_f32_16x16x32_bf16 v[26:29], v[142:145], v[190:193], v[26:29]
	v_mfma_f32_16x16x32_bf16 v[14:17], v[134:137], v[210:213], v[14:17]
	v_mfma_f32_16x16x32_bf16 v[10:13], v[142:145], v[210:213], v[10:13]
	v_mfma_f32_16x16x32_bf16 v[54:57], v[146:149], v[170:173], v[54:57]
	v_mfma_f32_16x16x32_bf16 v[50:53], v[154:157], v[170:173], v[50:53]
	v_mfma_f32_16x16x32_bf16 v[38:41], v[146:149], v[178:181], v[38:41]
	v_mfma_f32_16x16x32_bf16 v[34:37], v[154:157], v[178:181], v[34:37]
	v_mfma_f32_16x16x32_bf16 v[22:25], v[146:149], v[186:189], v[22:25]
	v_mfma_f32_16x16x32_bf16 v[18:21], v[154:157], v[186:189], v[18:21]
	v_mfma_f32_16x16x32_bf16 v[6:9], v[146:149], v[206:209], v[6:9]
	v_mfma_f32_16x16x32_bf16 v[2:5], v[154:157], v[206:209], v[2:5]
	v_mfma_f32_16x16x32_bf16 v[54:57], v[150:153], v[174:177], v[54:57]
	v_mfma_f32_16x16x32_bf16 v[50:53], v[166:169], v[174:177], v[50:53]
	v_mfma_f32_16x16x32_bf16 v[38:41], v[150:153], v[182:185], v[38:41]
	v_mfma_f32_16x16x32_bf16 v[34:37], v[166:169], v[182:185], v[34:37]
	v_mfma_f32_16x16x32_bf16 v[22:25], v[150:153], v[190:193], v[22:25]
	v_mfma_f32_16x16x32_bf16 v[18:21], v[166:169], v[190:193], v[18:21]
	v_mfma_f32_16x16x32_bf16 v[6:9], v[150:153], v[210:213], v[6:9]
	v_mfma_f32_16x16x32_bf16 v[2:5], v[166:169], v[210:213], v[2:5]
	s_barrier
	s_setprio 0
	s_add_i32 s30, 0, 0x18000
	s_add_i32 s31, 0, 0x1c000
	v_add_u32_e32 v142, s30, v204
	v_add_u32_e32 v166, s31, v204
	ds_read_b128 v[130:133], v142
	ds_read_b128 v[134:137], v142 offset:1024
	ds_read_b128 v[138:141], v142 offset:2048
	ds_read_b128 v[142:145], v142 offset:3072
	ds_read_b128 v[146:149], v166
	ds_read_b128 v[150:153], v166 offset:1024
	ds_read_b128 v[154:157], v166 offset:2048
	ds_read_b128 v[166:169], v166 offset:3072
	s_add_u32 s22, s22, 0x80000
	s_addc_u32 s23, s23, 0
	s_mov_b32 m0, s8
	v_lshl_add_u64 v[230:231], s[22:23], 0, v[158:159]
	ds_read_b128 v[170:173], v205 offset:32768
	ds_read_b128 v[174:177], v205 offset:33792
	ds_read_b128 v[178:181], v205 offset:34816
	ds_read_b128 v[182:185], v205 offset:35840
	ds_read_b128 v[186:189], v205 offset:36864
	ds_read_b128 v[190:193], v205 offset:37888
	ds_read_b128 v[206:209], v205 offset:38912
	ds_read_b128 v[210:213], v205 offset:39936
	global_load_lds_dwordx4 v[230:231], off
	v_lshl_add_u64 v[230:231], s[22:23], 0, v[160:161]
	s_mov_b32 m0, s9
	s_nop 0
	global_load_lds_dwordx4 v[230:231], off
	s_waitcnt vmcnt(8)
	s_waitcnt lgkmcnt(0)
	s_setprio 1
	s_barrier
	v_mfma_f32_16x16x32_bf16 v[126:129], v[130:133], v[170:173], v[126:129]
	v_mfma_f32_16x16x32_bf16 v[122:125], v[138:141], v[170:173], v[122:125]
	v_mfma_f32_16x16x32_bf16 v[110:113], v[130:133], v[178:181], v[110:113]
	v_mfma_f32_16x16x32_bf16 v[106:109], v[138:141], v[178:181], v[106:109]
	v_mfma_f32_16x16x32_bf16 v[94:97], v[130:133], v[186:189], v[94:97]
	v_mfma_f32_16x16x32_bf16 v[90:93], v[138:141], v[186:189], v[90:93]
	v_mfma_f32_16x16x32_bf16 v[78:81], v[130:133], v[206:209], v[78:81]
	v_mfma_f32_16x16x32_bf16 v[74:77], v[138:141], v[206:209], v[74:77]
	v_mfma_f32_16x16x32_bf16 v[126:129], v[134:137], v[174:177], v[126:129]
	v_mfma_f32_16x16x32_bf16 v[122:125], v[142:145], v[174:177], v[122:125]
	v_mfma_f32_16x16x32_bf16 v[110:113], v[134:137], v[182:185], v[110:113]
	v_mfma_f32_16x16x32_bf16 v[106:109], v[142:145], v[182:185], v[106:109]
	v_mfma_f32_16x16x32_bf16 v[94:97], v[134:137], v[190:193], v[94:97]
	v_mfma_f32_16x16x32_bf16 v[90:93], v[142:145], v[190:193], v[90:93]
	v_mfma_f32_16x16x32_bf16 v[78:81], v[134:137], v[210:213], v[78:81]
	v_mfma_f32_16x16x32_bf16 v[74:77], v[142:145], v[210:213], v[74:77]
	v_mfma_f32_16x16x32_bf16 v[118:121], v[146:149], v[170:173], v[118:121]
	v_mfma_f32_16x16x32_bf16 v[114:117], v[154:157], v[170:173], v[114:117]
	v_mfma_f32_16x16x32_bf16 v[102:105], v[146:149], v[178:181], v[102:105]
	v_mfma_f32_16x16x32_bf16 v[98:101], v[154:157], v[178:181], v[98:101]
	v_mfma_f32_16x16x32_bf16 v[86:89], v[146:149], v[186:189], v[86:89]
	v_mfma_f32_16x16x32_bf16 v[82:85], v[154:157], v[186:189], v[82:85]
	v_mfma_f32_16x16x32_bf16 v[70:73], v[146:149], v[206:209], v[70:73]
	v_mfma_f32_16x16x32_bf16 v[66:69], v[154:157], v[206:209], v[66:69]
	v_mfma_f32_16x16x32_bf16 v[118:121], v[150:153], v[174:177], v[118:121]
	v_mfma_f32_16x16x32_bf16 v[114:117], v[166:169], v[174:177], v[114:117]
	v_mfma_f32_16x16x32_bf16 v[102:105], v[150:153], v[182:185], v[102:105]
	v_mfma_f32_16x16x32_bf16 v[98:101], v[166:169], v[182:185], v[98:101]
	v_mfma_f32_16x16x32_bf16 v[86:89], v[150:153], v[190:193], v[86:89]
	v_mfma_f32_16x16x32_bf16 v[82:85], v[166:169], v[190:193], v[82:85]
	v_mfma_f32_16x16x32_bf16 v[70:73], v[150:153], v[210:213], v[70:73]
	v_mfma_f32_16x16x32_bf16 v[66:69], v[166:169], v[210:213], v[66:69]
	s_barrier
	s_setprio 0
	s_add_i32 s22, s30, s39
	v_lshl_add_u64 v[202:203], v[202:203], 0, s[10:11]
	s_mov_b32 m0, s22
	ds_read_b128 v[170:173], v205 offset:49152
	ds_read_b128 v[174:177], v205 offset:50176
	ds_read_b128 v[178:181], v205 offset:51200
	ds_read_b128 v[182:185], v205 offset:52224
	ds_read_b128 v[186:189], v205 offset:53248
	ds_read_b128 v[190:193], v205 offset:54272
	ds_read_b128 v[206:209], v205 offset:55296
	ds_read_b128 v[210:213], v205 offset:56320
	global_load_lds_dwordx4 v[202:203], off
	s_add_i32 m0, s22, 0x2000
	s_add_u32 s20, s20, 0x80080
	v_lshl_add_u64 v[202:203], v[214:215], 0, s[10:11]
	s_addc_u32 s21, s21, 0
	s_add_i32 s22, s31, s39
	global_load_lds_dwordx4 v[202:203], off
	v_lshl_add_u64 v[202:203], s[20:21], 0, v[158:159]
	s_mov_b32 m0, s22
	s_nop 0
	global_load_lds_dwordx4 v[202:203], off
	v_lshl_add_u64 v[202:203], s[20:21], 0, v[160:161]
	s_add_i32 m0, s22, 0x2000
	s_nop 0
	global_load_lds_dwordx4 v[202:203], off
	v_lshl_add_u64 v[202:203], v[216:217], 0, s[10:11]
	s_mov_b32 m0, s56
	s_nop 0
	global_load_lds_dwordx4 v[202:203], off
	v_lshl_add_u64 v[202:203], v[228:229], 0, s[10:11]
	s_mov_b32 m0, s57
	s_nop 0
	global_load_lds_dwordx4 v[202:203], off
	s_waitcnt vmcnt(8)
	s_waitcnt lgkmcnt(0)
	s_setprio 1
	s_barrier
	v_mfma_f32_16x16x32_bf16 v[62:65], v[130:133], v[170:173], v[62:65]
	v_mfma_f32_16x16x32_bf16 v[58:61], v[138:141], v[170:173], v[58:61]
	v_mfma_f32_16x16x32_bf16 v[46:49], v[130:133], v[178:181], v[46:49]
	v_mfma_f32_16x16x32_bf16 v[42:45], v[138:141], v[178:181], v[42:45]
	v_mfma_f32_16x16x32_bf16 v[30:33], v[130:133], v[186:189], v[30:33]
	v_mfma_f32_16x16x32_bf16 v[26:29], v[138:141], v[186:189], v[26:29]
	v_mfma_f32_16x16x32_bf16 v[14:17], v[130:133], v[206:209], v[14:17]
	v_mfma_f32_16x16x32_bf16 v[10:13], v[138:141], v[206:209], v[10:13]
	v_mfma_f32_16x16x32_bf16 v[62:65], v[134:137], v[174:177], v[62:65]
	v_mfma_f32_16x16x32_bf16 v[58:61], v[142:145], v[174:177], v[58:61]
	v_mfma_f32_16x16x32_bf16 v[46:49], v[134:137], v[182:185], v[46:49]
	v_mfma_f32_16x16x32_bf16 v[42:45], v[142:145], v[182:185], v[42:45]
	v_mfma_f32_16x16x32_bf16 v[30:33], v[134:137], v[190:193], v[30:33]
	v_mfma_f32_16x16x32_bf16 v[26:29], v[142:145], v[190:193], v[26:29]
	v_mfma_f32_16x16x32_bf16 v[14:17], v[134:137], v[210:213], v[14:17]
	v_mfma_f32_16x16x32_bf16 v[10:13], v[142:145], v[210:213], v[10:13]
	v_mfma_f32_16x16x32_bf16 v[54:57], v[146:149], v[170:173], v[54:57]
	v_mfma_f32_16x16x32_bf16 v[50:53], v[154:157], v[170:173], v[50:53]
	v_mfma_f32_16x16x32_bf16 v[38:41], v[146:149], v[178:181], v[38:41]
	v_mfma_f32_16x16x32_bf16 v[34:37], v[154:157], v[178:181], v[34:37]
	v_mfma_f32_16x16x32_bf16 v[22:25], v[146:149], v[186:189], v[22:25]
	v_mfma_f32_16x16x32_bf16 v[18:21], v[154:157], v[186:189], v[18:21]
	v_mfma_f32_16x16x32_bf16 v[6:9], v[146:149], v[206:209], v[6:9]
	v_mfma_f32_16x16x32_bf16 v[2:5], v[154:157], v[206:209], v[2:5]
	v_mfma_f32_16x16x32_bf16 v[54:57], v[150:153], v[174:177], v[54:57]
	v_mfma_f32_16x16x32_bf16 v[50:53], v[166:169], v[174:177], v[50:53]
	v_mfma_f32_16x16x32_bf16 v[38:41], v[150:153], v[182:185], v[38:41]
	v_mfma_f32_16x16x32_bf16 v[34:37], v[166:169], v[182:185], v[34:37]
	v_mfma_f32_16x16x32_bf16 v[22:25], v[150:153], v[190:193], v[22:25]
	v_mfma_f32_16x16x32_bf16 v[18:21], v[166:169], v[190:193], v[18:21]
	v_mfma_f32_16x16x32_bf16 v[6:9], v[150:153], v[210:213], v[6:9]
	v_mfma_f32_16x16x32_bf16 v[2:5], v[166:169], v[210:213], v[2:5]
	s_barrier
	s_setprio 0
	s_add_i32 s29, s29, 2
	s_add_u32 s18, s18, 0x100
	s_addc_u32 s19, s19, 0
	s_add_u32 s27, s27, 0x100
	s_addc_u32 s28, s28, 0
	s_cmp_gt_u32 s29, 29
	s_cbranch_scc0 .LBB0_364
	s_and_b64 vcc, exec, s[58:59]
	s_cbranch_vccz .LBB0_367
	s_barrier

.LBB0_986:
	s_add_u32 s24, s22, 0x100
	s_addc_u32 s25, s23, 0
	s_add_i32 s62, 0, 0x10000
	s_cmp_eq_u32 s61, 28
	s_cselect_b32 s29, s17, s25
	s_cselect_b32 s28, s58, s24
	v_add_u32_e32 v138, s62, v140
	s_cselect_b32 s27, s19, s60
	s_cselect_b32 s26, s18, s59
	s_add_i32 s63, 0, 0x14000
	ds_read_b128 v[142:145], v138
	ds_read_b128 v[146:149], v138 offset:1024
	ds_read_b128 v[150:153], v138 offset:2048
	ds_read_b128 v[154:157], v138 offset:3072
	v_add_u32_e32 v138, s63, v140
	ds_read_b128 v[158:161], v138
	ds_read_b128 v[162:165], v138 offset:1024
	ds_read_b128 v[166:169], v138 offset:2048
	ds_read_b128 v[170:173], v138 offset:3072
	v_lshl_add_u64 v[138:139], s[22:23], 0, v[134:135]
	s_add_i32 m0, s47, 0xc000
	ds_read_b128 v[174:177], v141
	ds_read_b128 v[178:181], v141 offset:1024
	ds_read_b128 v[182:185], v141 offset:2048
	ds_read_b128 v[186:189], v141 offset:3072
	ds_read_b128 v[190:193], v141 offset:4096
	ds_read_b128 v[202:205], v141 offset:5120
	ds_read_b128 v[206:209], v141 offset:6144
	ds_read_b128 v[210:213], v141 offset:7168
	global_load_lds_dwordx4 v[138:139], off
	v_lshl_add_u64 v[138:139], s[22:23], 0, v[136:137]
	s_add_i32 m0, s47, 0xe000
	s_nop 0
	global_load_lds_dwordx4 v[138:139], off
	s_waitcnt vmcnt(8)
	s_waitcnt lgkmcnt(0)
	s_setprio 1
	s_barrier
	v_mfma_f32_16x16x32_bf16 v[126:129], v[142:145], v[174:177], v[126:129]
	v_mfma_f32_16x16x32_bf16 v[122:125], v[150:153], v[174:177], v[122:125]
	v_mfma_f32_16x16x32_bf16 v[118:121], v[142:145], v[182:185], v[118:121]
	v_mfma_f32_16x16x32_bf16 v[110:113], v[150:153], v[182:185], v[110:113]
	v_mfma_f32_16x16x32_bf16 v[102:105], v[142:145], v[190:193], v[102:105]
	v_mfma_f32_16x16x32_bf16 v[94:97], v[150:153], v[190:193], v[94:97]
	v_mfma_f32_16x16x32_bf16 v[86:89], v[142:145], v[206:209], v[86:89]
	v_mfma_f32_16x16x32_bf16 v[78:81], v[150:153], v[206:209], v[78:81]
	v_mfma_f32_16x16x32_bf16 v[126:129], v[146:149], v[178:181], v[126:129]
	v_mfma_f32_16x16x32_bf16 v[122:125], v[154:157], v[178:181], v[122:125]
	v_mfma_f32_16x16x32_bf16 v[118:121], v[146:149], v[186:189], v[118:121]
	v_mfma_f32_16x16x32_bf16 v[110:113], v[154:157], v[186:189], v[110:113]
	v_mfma_f32_16x16x32_bf16 v[102:105], v[146:149], v[202:205], v[102:105]
	v_mfma_f32_16x16x32_bf16 v[94:97], v[154:157], v[202:205], v[94:97]
	v_mfma_f32_16x16x32_bf16 v[86:89], v[146:149], v[210:213], v[86:89]
	v_mfma_f32_16x16x32_bf16 v[78:81], v[154:157], v[210:213], v[78:81]
	v_mfma_f32_16x16x32_bf16 v[114:117], v[158:161], v[174:177], v[114:117]
	v_mfma_f32_16x16x32_bf16 v[106:109], v[166:169], v[174:177], v[106:109]
	v_mfma_f32_16x16x32_bf16 v[98:101], v[158:161], v[182:185], v[98:101]
	v_mfma_f32_16x16x32_bf16 v[90:93], v[166:169], v[182:185], v[90:93]
	v_mfma_f32_16x16x32_bf16 v[82:85], v[158:161], v[190:193], v[82:85]
	v_mfma_f32_16x16x32_bf16 v[74:77], v[166:169], v[190:193], v[74:77]
	v_mfma_f32_16x16x32_bf16 v[70:73], v[158:161], v[206:209], v[70:73]
	v_mfma_f32_16x16x32_bf16 v[66:69], v[166:169], v[206:209], v[66:69]
	v_mfma_f32_16x16x32_bf16 v[114:117], v[162:165], v[178:181], v[114:117]
	v_mfma_f32_16x16x32_bf16 v[106:109], v[170:173], v[178:181], v[106:109]
	v_mfma_f32_16x16x32_bf16 v[98:101], v[162:165], v[186:189], v[98:101]
	v_mfma_f32_16x16x32_bf16 v[90:93], v[170:173], v[186:189], v[90:93]
	v_mfma_f32_16x16x32_bf16 v[82:85], v[162:165], v[202:205], v[82:85]
	v_mfma_f32_16x16x32_bf16 v[74:77], v[170:173], v[202:205], v[74:77]
	v_mfma_f32_16x16x32_bf16 v[70:73], v[162:165], v[210:213], v[70:73]
	v_mfma_f32_16x16x32_bf16 v[66:69], v[170:173], v[210:213], v[66:69]
	s_barrier
	s_setprio 0
	s_add_i32 s22, s62, s36
	v_lshl_add_u64 v[138:139], s[26:27], 0, v[132:133]
	s_mov_b32 m0, s22
	ds_read_b128 v[174:177], v141 offset:16384
	ds_read_b128 v[178:181], v141 offset:17408
	ds_read_b128 v[182:185], v141 offset:18432
	ds_read_b128 v[186:189], v141 offset:19456
	ds_read_b128 v[190:193], v141 offset:20480
	ds_read_b128 v[202:205], v141 offset:21504
	ds_read_b128 v[206:209], v141 offset:22528
	ds_read_b128 v[210:213], v141 offset:23552
	global_load_lds_dwordx4 v[138:139], off
	s_add_i32 m0, s22, 0x2000
	s_add_u32 s22, s26, 0x80000
	v_lshl_add_u64 v[214:215], s[26:27], 0, v[130:131]
	s_addc_u32 s23, s27, 0
	s_add_i32 s62, s63, s36
	global_load_lds_dwordx4 v[214:215], off
	v_lshl_add_u64 v[216:217], s[22:23], 0, v[132:133]
	s_mov_b32 m0, s62
	v_lshl_add_u64 v[228:229], s[28:29], 0, v[130:131]
	global_load_lds_dwordx4 v[216:217], off
	v_lshl_add_u64 v[216:217], s[22:23], 0, v[130:131]
	s_add_i32 m0, s62, 0x2000
	s_nop 0
	global_load_lds_dwordx4 v[216:217], off
	v_lshl_add_u64 v[216:217], s[28:29], 0, v[132:133]
	s_mov_b32 m0, s47
	s_nop 0
	global_load_lds_dwordx4 v[216:217], off
	s_mov_b32 m0, s48
	s_nop 0
	global_load_lds_dwordx4 v[228:229], off
	s_waitcnt vmcnt(8)
	s_waitcnt lgkmcnt(0)
	s_setprio 1
	s_barrier
	v_mfma_f32_16x16x32_bf16 v[62:65], v[142:145], v[174:177], v[62:65]
	v_mfma_f32_16x16x32_bf16 v[58:61], v[150:153], v[174:177], v[58:61]
	v_mfma_f32_16x16x32_bf16 v[54:57], v[142:145], v[182:185], v[54:57]
	v_mfma_f32_16x16x32_bf16 v[46:49], v[150:153], v[182:185], v[46:49]
	v_mfma_f32_16x16x32_bf16 v[38:41], v[142:145], v[190:193], v[38:41]
	v_mfma_f32_16x16x32_bf16 v[30:33], v[150:153], v[190:193], v[30:33]
	v_mfma_f32_16x16x32_bf16 v[22:25], v[142:145], v[206:209], v[22:25]
	v_mfma_f32_16x16x32_bf16 v[14:17], v[150:153], v[206:209], v[14:17]
	v_mfma_f32_16x16x32_bf16 v[62:65], v[146:149], v[178:181], v[62:65]
	v_mfma_f32_16x16x32_bf16 v[58:61], v[154:157], v[178:181], v[58:61]
	v_mfma_f32_16x16x32_bf16 v[54:57], v[146:149], v[186:189], v[54:57]
	v_mfma_f32_16x16x32_bf16 v[46:49], v[154:157], v[186:189], v[46:49]
	v_mfma_f32_16x16x32_bf16 v[38:41], v[146:149], v[202:205], v[38:41]
	v_mfma_f32_16x16x32_bf16 v[30:33], v[154:157], v[202:205], v[30:33]
	v_mfma_f32_16x16x32_bf16 v[22:25], v[146:149], v[210:213], v[22:25]
	v_mfma_f32_16x16x32_bf16 v[14:17], v[154:157], v[210:213], v[14:17]
	v_mfma_f32_16x16x32_bf16 v[50:53], v[158:161], v[174:177], v[50:53]
	v_mfma_f32_16x16x32_bf16 v[42:45], v[166:169], v[174:177], v[42:45]
	v_mfma_f32_16x16x32_bf16 v[34:37], v[158:161], v[182:185], v[34:37]
	v_mfma_f32_16x16x32_bf16 v[26:29], v[166:169], v[182:185], v[26:29]
	v_mfma_f32_16x16x32_bf16 v[18:21], v[158:161], v[190:193], v[18:21]
	v_mfma_f32_16x16x32_bf16 v[10:13], v[166:169], v[190:193], v[10:13]
	v_mfma_f32_16x16x32_bf16 v[6:9], v[158:161], v[206:209], v[6:9]
	v_mfma_f32_16x16x32_bf16 v[2:5], v[166:169], v[206:209], v[2:5]
	v_mfma_f32_16x16x32_bf16 v[50:53], v[162:165], v[178:181], v[50:53]
	v_mfma_f32_16x16x32_bf16 v[42:45], v[170:173], v[178:181], v[42:45]
	v_mfma_f32_16x16x32_bf16 v[34:37], v[162:165], v[186:189], v[34:37]
	v_mfma_f32_16x16x32_bf16 v[26:29], v[170:173], v[186:189], v[26:29]
	v_mfma_f32_16x16x32_bf16 v[18:21], v[162:165], v[202:205], v[18:21]
	v_mfma_f32_16x16x32_bf16 v[10:13], v[170:173], v[202:205], v[10:13]
	v_mfma_f32_16x16x32_bf16 v[6:9], v[162:165], v[210:213], v[6:9]
	v_mfma_f32_16x16x32_bf16 v[2:5], v[170:173], v[210:213], v[2:5]
	s_barrier
	s_setprio 0
	s_add_i32 s62, 0, 0x18000
	s_add_i32 s63, 0, 0x1c000
	v_add_u32_e32 v154, s62, v140
	v_add_u32_e32 v170, s63, v140
	ds_read_b128 v[142:145], v154
	ds_read_b128 v[146:149], v154 offset:1024
	ds_read_b128 v[150:153], v154 offset:2048
	ds_read_b128 v[154:157], v154 offset:3072
	ds_read_b128 v[158:161], v170
	ds_read_b128 v[162:165], v170 offset:1024
	ds_read_b128 v[166:169], v170 offset:2048
	ds_read_b128 v[170:173], v170 offset:3072
	s_add_u32 s22, s28, 0x80000
	s_addc_u32 s23, s29, 0
	s_mov_b32 m0, s49
	v_lshl_add_u64 v[230:231], s[22:23], 0, v[132:133]
	ds_read_b128 v[174:177], v141 offset:32768
	ds_read_b128 v[178:181], v141 offset:33792
	ds_read_b128 v[182:185], v141 offset:34816
	ds_read_b128 v[186:189], v141 offset:35840
	ds_read_b128 v[190:193], v141 offset:36864
	ds_read_b128 v[202:205], v141 offset:37888
	ds_read_b128 v[206:209], v141 offset:38912
	ds_read_b128 v[210:213], v141 offset:39936
	global_load_lds_dwordx4 v[230:231], off
	v_lshl_add_u64 v[230:231], s[22:23], 0, v[130:131]
	s_mov_b32 m0, s50
	s_nop 0
	global_load_lds_dwordx4 v[230:231], off
	s_waitcnt vmcnt(8)
	s_waitcnt lgkmcnt(0)
	s_setprio 1
	s_barrier
	v_mfma_f32_16x16x32_bf16 v[126:129], v[142:145], v[174:177], v[126:129]
	v_mfma_f32_16x16x32_bf16 v[122:125], v[150:153], v[174:177], v[122:125]
	v_mfma_f32_16x16x32_bf16 v[118:121], v[142:145], v[182:185], v[118:121]
	v_mfma_f32_16x16x32_bf16 v[110:113], v[150:153], v[182:185], v[110:113]
	v_mfma_f32_16x16x32_bf16 v[102:105], v[142:145], v[190:193], v[102:105]
	v_mfma_f32_16x16x32_bf16 v[94:97], v[150:153], v[190:193], v[94:97]
	v_mfma_f32_16x16x32_bf16 v[86:89], v[142:145], v[206:209], v[86:89]
	v_mfma_f32_16x16x32_bf16 v[78:81], v[150:153], v[206:209], v[78:81]
	v_mfma_f32_16x16x32_bf16 v[126:129], v[146:149], v[178:181], v[126:129]
	v_mfma_f32_16x16x32_bf16 v[122:125], v[154:157], v[178:181], v[122:125]
	v_mfma_f32_16x16x32_bf16 v[118:121], v[146:149], v[186:189], v[118:121]
	v_mfma_f32_16x16x32_bf16 v[110:113], v[154:157], v[186:189], v[110:113]
	v_mfma_f32_16x16x32_bf16 v[102:105], v[146:149], v[202:205], v[102:105]
	v_mfma_f32_16x16x32_bf16 v[94:97], v[154:157], v[202:205], v[94:97]
	v_mfma_f32_16x16x32_bf16 v[86:89], v[146:149], v[210:213], v[86:89]
	v_mfma_f32_16x16x32_bf16 v[78:81], v[154:157], v[210:213], v[78:81]
	v_mfma_f32_16x16x32_bf16 v[114:117], v[158:161], v[174:177], v[114:117]
	v_mfma_f32_16x16x32_bf16 v[106:109], v[166:169], v[174:177], v[106:109]
	v_mfma_f32_16x16x32_bf16 v[98:101], v[158:161], v[182:185], v[98:101]
	v_mfma_f32_16x16x32_bf16 v[90:93], v[166:169], v[182:185], v[90:93]
	v_mfma_f32_16x16x32_bf16 v[82:85], v[158:161], v[190:193], v[82:85]
	v_mfma_f32_16x16x32_bf16 v[74:77], v[166:169], v[190:193], v[74:77]
	v_mfma_f32_16x16x32_bf16 v[70:73], v[158:161], v[206:209], v[70:73]
	v_mfma_f32_16x16x32_bf16 v[66:69], v[166:169], v[206:209], v[66:69]
	v_mfma_f32_16x16x32_bf16 v[114:117], v[162:165], v[178:181], v[114:117]
	v_mfma_f32_16x16x32_bf16 v[106:109], v[170:173], v[178:181], v[106:109]
	v_mfma_f32_16x16x32_bf16 v[98:101], v[162:165], v[186:189], v[98:101]
	v_mfma_f32_16x16x32_bf16 v[90:93], v[170:173], v[186:189], v[90:93]
	v_mfma_f32_16x16x32_bf16 v[82:85], v[162:165], v[202:205], v[82:85]
	v_mfma_f32_16x16x32_bf16 v[74:77], v[170:173], v[202:205], v[74:77]
	v_mfma_f32_16x16x32_bf16 v[70:73], v[162:165], v[210:213], v[70:73]
	v_mfma_f32_16x16x32_bf16 v[66:69], v[170:173], v[210:213], v[66:69]
	s_barrier
	s_setprio 0
	s_add_i32 s22, s62, s36
	v_lshl_add_u64 v[138:139], v[138:139], 0, s[10:11]
	s_mov_b32 m0, s22
	ds_read_b128 v[174:177], v141 offset:49152
	ds_read_b128 v[178:181], v141 offset:50176
	ds_read_b128 v[182:185], v141 offset:51200
	ds_read_b128 v[186:189], v141 offset:52224
	ds_read_b128 v[190:193], v141 offset:53248
	ds_read_b128 v[202:205], v141 offset:54272
	ds_read_b128 v[206:209], v141 offset:55296
	ds_read_b128 v[210:213], v141 offset:56320
	global_load_lds_dwordx4 v[138:139], off
	s_add_i32 m0, s22, 0x2000
	s_add_u32 s22, s26, 0x80080
	v_lshl_add_u64 v[138:139], v[214:215], 0, s[10:11]
	s_addc_u32 s23, s27, 0
	s_add_i32 s26, s63, s36
	global_load_lds_dwordx4 v[138:139], off
	v_lshl_add_u64 v[138:139], s[22:23], 0, v[132:133]
	s_mov_b32 m0, s26
	s_nop 0
	global_load_lds_dwordx4 v[138:139], off
	v_lshl_add_u64 v[138:139], s[22:23], 0, v[130:131]
	s_add_i32 m0, s26, 0x2000
	s_nop 0
	global_load_lds_dwordx4 v[138:139], off
	v_lshl_add_u64 v[138:139], v[216:217], 0, s[10:11]
	s_mov_b32 m0, s51
	s_nop 0
	global_load_lds_dwordx4 v[138:139], off
	v_lshl_add_u64 v[138:139], v[228:229], 0, s[10:11]
	s_mov_b32 m0, s52
	s_nop 0
	global_load_lds_dwordx4 v[138:139], off
	s_waitcnt vmcnt(8)
	s_waitcnt lgkmcnt(0)
	s_setprio 1
	s_barrier
	v_mfma_f32_16x16x32_bf16 v[62:65], v[142:145], v[174:177], v[62:65]
	v_mfma_f32_16x16x32_bf16 v[58:61], v[150:153], v[174:177], v[58:61]
	v_mfma_f32_16x16x32_bf16 v[54:57], v[142:145], v[182:185], v[54:57]
	v_mfma_f32_16x16x32_bf16 v[46:49], v[150:153], v[182:185], v[46:49]
	v_mfma_f32_16x16x32_bf16 v[38:41], v[142:145], v[190:193], v[38:41]
	v_mfma_f32_16x16x32_bf16 v[30:33], v[150:153], v[190:193], v[30:33]
	v_mfma_f32_16x16x32_bf16 v[22:25], v[142:145], v[206:209], v[22:25]
	v_mfma_f32_16x16x32_bf16 v[14:17], v[150:153], v[206:209], v[14:17]
	v_mfma_f32_16x16x32_bf16 v[62:65], v[146:149], v[178:181], v[62:65]
	v_mfma_f32_16x16x32_bf16 v[58:61], v[154:157], v[178:181], v[58:61]
	v_mfma_f32_16x16x32_bf16 v[54:57], v[146:149], v[186:189], v[54:57]
	v_mfma_f32_16x16x32_bf16 v[46:49], v[154:157], v[186:189], v[46:49]
	v_mfma_f32_16x16x32_bf16 v[38:41], v[146:149], v[202:205], v[38:41]
	v_mfma_f32_16x16x32_bf16 v[30:33], v[154:157], v[202:205], v[30:33]
	v_mfma_f32_16x16x32_bf16 v[22:25], v[146:149], v[210:213], v[22:25]
	v_mfma_f32_16x16x32_bf16 v[14:17], v[154:157], v[210:213], v[14:17]
	v_mfma_f32_16x16x32_bf16 v[50:53], v[158:161], v[174:177], v[50:53]
	v_mfma_f32_16x16x32_bf16 v[42:45], v[166:169], v[174:177], v[42:45]
	v_mfma_f32_16x16x32_bf16 v[34:37], v[158:161], v[182:185], v[34:37]
	v_mfma_f32_16x16x32_bf16 v[26:29], v[166:169], v[182:185], v[26:29]
	v_mfma_f32_16x16x32_bf16 v[18:21], v[158:161], v[190:193], v[18:21]
	v_mfma_f32_16x16x32_bf16 v[10:13], v[166:169], v[190:193], v[10:13]
	v_mfma_f32_16x16x32_bf16 v[6:9], v[158:161], v[206:209], v[6:9]
	v_mfma_f32_16x16x32_bf16 v[2:5], v[166:169], v[206:209], v[2:5]
	v_mfma_f32_16x16x32_bf16 v[50:53], v[162:165], v[178:181], v[50:53]
	v_mfma_f32_16x16x32_bf16 v[42:45], v[170:173], v[178:181], v[42:45]
	v_mfma_f32_16x16x32_bf16 v[34:37], v[162:165], v[186:189], v[34:37]
	v_mfma_f32_16x16x32_bf16 v[26:29], v[170:173], v[186:189], v[26:29]
	v_mfma_f32_16x16x32_bf16 v[18:21], v[162:165], v[202:205], v[18:21]
	v_mfma_f32_16x16x32_bf16 v[10:13], v[170:173], v[202:205], v[10:13]
	v_mfma_f32_16x16x32_bf16 v[6:9], v[162:165], v[210:213], v[6:9]
	v_mfma_f32_16x16x32_bf16 v[2:5], v[170:173], v[210:213], v[2:5]
	s_barrier
	s_setprio 0
	s_add_i32 s61, s61, 2
	s_add_u32 s59, s59, 0x100
	s_addc_u32 s60, s60, 0
	s_cmp_gt_u32 s61, 29
	s_mov_b64 s[22:23], s[24:25]
	s_cbranch_scc0 .LBB0_986
	s_and_b64 vcc, exec, s[14:15]
	s_cbranch_vccz .LBB0_989
	s_barrier

.LBB0_1002:
	s_add_i32 s36, s21, 0x100
	s_and_b64 s[30:31], s[28:29], exec
	s_cselect_b32 s31, 0, s36
	s_cselect_b32 s30, 0, 0
	s_add_u32 s36, s8, s31
	s_addc_u32 s37, s9, s30
	s_add_u32 s30, s24, s21
	s_addc_u32 s31, s25, 0
	s_add_u32 s30, s30, 0x100
	s_addc_u32 s31, s31, 0
	s_add_i32 s71, 0, 0x10000
	s_and_b64 s[28:29], s[28:29], exec
	s_cselect_b32 s39, s19, s31
	s_cselect_b32 s38, s18, s30
	s_add_i32 s29, 0, 0x14000
	s_add_u32 s21, s44, s21
	s_addc_u32 s28, s45, 0
	s_add_u32 s48, s21, 0x17110080
	s_addc_u32 s49, s28, 0
	s_add_i32 s70, s71, s52
	s_add_i32 m0, s53, 0xc000
	s_add_i32 s73, s53, 0xe000
	s_add_i32 s67, s70, 0x2000
	v_add_u32_e32 v134, s71, v136
	s_add_u32 s46, s38, 0x10000
	ds_read_b128 v[138:141], v134
	ds_read_b128 v[142:145], v134 offset:1024
	ds_read_b128 v[146:149], v134 offset:2048
	ds_read_b128 v[150:153], v134 offset:3072
	v_add_u32_e32 v134, s29, v136
	s_addc_u32 s47, s39, 0
	s_add_i32 s69, s29, s52
	ds_read_b128 v[154:157], v134
	ds_read_b128 v[158:161], v134 offset:1024
	ds_read_b128 v[162:165], v134 offset:2048
	ds_read_b128 v[166:169], v134 offset:3072
	s_add_i32 s68, s69, 0x2000
	s_add_i32 s66, 0, 0x18000
	s_add_i32 s65, 0, 0x1c000
	s_add_u32 s30, s36, 0x10000
	s_addc_u32 s31, s37, 0
	s_add_i32 s64, s66, s52
	s_add_i32 s21, s64, 0x2000
	s_add_u32 s28, s38, 0x10080
	s_addc_u32 s29, s39, 0
	s_add_i32 s72, s65, s52
	s_add_i32 s71, s72, 0x2000
	v_lshl_add_u64 v[134:135], s[48:49], 0, v[132:133]
	ds_read_b128 v[170:173], v137
	ds_read_b128 v[174:177], v137 offset:1024
	ds_read_b128 v[178:181], v137 offset:2048
	ds_read_b128 v[182:185], v137 offset:3072
	ds_read_b128 v[186:189], v137 offset:4096
	ds_read_b128 v[190:193], v137 offset:5120
	ds_read_b128 v[202:205], v137 offset:6144
	ds_read_b128 v[206:209], v137 offset:7168
	global_load_lds_dwordx4 v[134:135], off
	v_lshl_add_u64 v[134:135], s[48:49], 0, v[130:131]
	s_mov_b32 m0, s73
	s_nop 0
	global_load_lds_dwordx4 v[134:135], off
	s_waitcnt vmcnt(8)
	s_waitcnt lgkmcnt(0)
	s_setprio 1
	s_barrier
	v_mfma_f32_16x16x32_bf16 v[126:129], v[138:141], v[170:173], v[126:129]
	v_mfma_f32_16x16x32_bf16 v[122:125], v[146:149], v[170:173], v[122:125]
	v_mfma_f32_16x16x32_bf16 v[118:121], v[138:141], v[178:181], v[118:121]
	v_mfma_f32_16x16x32_bf16 v[110:113], v[146:149], v[178:181], v[110:113]
	v_mfma_f32_16x16x32_bf16 v[102:105], v[138:141], v[186:189], v[102:105]
	v_mfma_f32_16x16x32_bf16 v[94:97], v[146:149], v[186:189], v[94:97]
	v_mfma_f32_16x16x32_bf16 v[86:89], v[138:141], v[202:205], v[86:89]
	v_mfma_f32_16x16x32_bf16 v[78:81], v[146:149], v[202:205], v[78:81]
	v_mfma_f32_16x16x32_bf16 v[126:129], v[142:145], v[174:177], v[126:129]
	v_mfma_f32_16x16x32_bf16 v[122:125], v[150:153], v[174:177], v[122:125]
	v_mfma_f32_16x16x32_bf16 v[118:121], v[142:145], v[182:185], v[118:121]
	v_mfma_f32_16x16x32_bf16 v[110:113], v[150:153], v[182:185], v[110:113]
	v_mfma_f32_16x16x32_bf16 v[102:105], v[142:145], v[190:193], v[102:105]
	v_mfma_f32_16x16x32_bf16 v[94:97], v[150:153], v[190:193], v[94:97]
	v_mfma_f32_16x16x32_bf16 v[86:89], v[142:145], v[206:209], v[86:89]
	v_mfma_f32_16x16x32_bf16 v[78:81], v[150:153], v[206:209], v[78:81]
	v_mfma_f32_16x16x32_bf16 v[114:117], v[154:157], v[170:173], v[114:117]
	v_mfma_f32_16x16x32_bf16 v[106:109], v[162:165], v[170:173], v[106:109]
	v_mfma_f32_16x16x32_bf16 v[98:101], v[154:157], v[178:181], v[98:101]
	v_mfma_f32_16x16x32_bf16 v[90:93], v[162:165], v[178:181], v[90:93]
	v_mfma_f32_16x16x32_bf16 v[82:85], v[154:157], v[186:189], v[82:85]
	v_mfma_f32_16x16x32_bf16 v[74:77], v[162:165], v[186:189], v[74:77]
	v_mfma_f32_16x16x32_bf16 v[70:73], v[154:157], v[202:205], v[70:73]
	v_mfma_f32_16x16x32_bf16 v[66:69], v[162:165], v[202:205], v[66:69]
	v_mfma_f32_16x16x32_bf16 v[114:117], v[158:161], v[174:177], v[114:117]
	v_mfma_f32_16x16x32_bf16 v[106:109], v[166:169], v[174:177], v[106:109]
	v_mfma_f32_16x16x32_bf16 v[98:101], v[158:161], v[182:185], v[98:101]
	v_mfma_f32_16x16x32_bf16 v[90:93], v[166:169], v[182:185], v[90:93]
	v_mfma_f32_16x16x32_bf16 v[82:85], v[158:161], v[190:193], v[82:85]
	v_mfma_f32_16x16x32_bf16 v[74:77], v[166:169], v[190:193], v[74:77]
	v_mfma_f32_16x16x32_bf16 v[70:73], v[158:161], v[206:209], v[70:73]
	v_mfma_f32_16x16x32_bf16 v[66:69], v[166:169], v[206:209], v[66:69]
	s_barrier
	s_setprio 0
	s_mov_b32 m0, s70
	v_lshl_add_u64 v[134:135], s[38:39], 0, v[132:133]
	ds_read_b128 v[170:173], v137 offset:16384
	ds_read_b128 v[174:177], v137 offset:17408
	ds_read_b128 v[178:181], v137 offset:18432
	ds_read_b128 v[182:185], v137 offset:19456
	ds_read_b128 v[186:189], v137 offset:20480
	ds_read_b128 v[190:193], v137 offset:21504
	ds_read_b128 v[202:205], v137 offset:22528
	ds_read_b128 v[206:209], v137 offset:23552
	global_load_lds_dwordx4 v[134:135], off
	v_lshl_add_u64 v[210:211], s[38:39], 0, v[130:131]
	s_mov_b32 m0, s67
	v_lshl_add_u64 v[212:213], s[46:47], 0, v[132:133]
	global_load_lds_dwordx4 v[210:211], off
	s_mov_b32 m0, s69
	v_lshl_add_u64 v[214:215], s[36:37], 0, v[130:131]
	global_load_lds_dwordx4 v[212:213], off
	v_lshl_add_u64 v[212:213], s[46:47], 0, v[130:131]
	s_mov_b32 m0, s68
	s_nop 0
	global_load_lds_dwordx4 v[212:213], off
	v_lshl_add_u64 v[212:213], s[36:37], 0, v[132:133]
	s_mov_b32 m0, s53
	s_nop 0
	global_load_lds_dwordx4 v[212:213], off
	s_mov_b32 m0, s56
	s_nop 0
	global_load_lds_dwordx4 v[214:215], off
	s_waitcnt vmcnt(8)
	s_waitcnt lgkmcnt(0)
	s_setprio 1
	s_barrier
	v_mfma_f32_16x16x32_bf16 v[62:65], v[138:141], v[170:173], v[62:65]
	v_mfma_f32_16x16x32_bf16 v[58:61], v[146:149], v[170:173], v[58:61]
	v_mfma_f32_16x16x32_bf16 v[54:57], v[138:141], v[178:181], v[54:57]
	v_mfma_f32_16x16x32_bf16 v[46:49], v[146:149], v[178:181], v[46:49]
	v_mfma_f32_16x16x32_bf16 v[38:41], v[138:141], v[186:189], v[38:41]
	v_mfma_f32_16x16x32_bf16 v[30:33], v[146:149], v[186:189], v[30:33]
	v_mfma_f32_16x16x32_bf16 v[22:25], v[138:141], v[202:205], v[22:25]
	v_mfma_f32_16x16x32_bf16 v[14:17], v[146:149], v[202:205], v[14:17]
	v_mfma_f32_16x16x32_bf16 v[62:65], v[142:145], v[174:177], v[62:65]
	v_mfma_f32_16x16x32_bf16 v[58:61], v[150:153], v[174:177], v[58:61]
	v_mfma_f32_16x16x32_bf16 v[54:57], v[142:145], v[182:185], v[54:57]
	v_mfma_f32_16x16x32_bf16 v[46:49], v[150:153], v[182:185], v[46:49]
	v_mfma_f32_16x16x32_bf16 v[38:41], v[142:145], v[190:193], v[38:41]
	v_mfma_f32_16x16x32_bf16 v[30:33], v[150:153], v[190:193], v[30:33]
	v_mfma_f32_16x16x32_bf16 v[22:25], v[142:145], v[206:209], v[22:25]
	v_mfma_f32_16x16x32_bf16 v[14:17], v[150:153], v[206:209], v[14:17]
	v_mfma_f32_16x16x32_bf16 v[50:53], v[154:157], v[170:173], v[50:53]
	v_mfma_f32_16x16x32_bf16 v[42:45], v[162:165], v[170:173], v[42:45]
	v_mfma_f32_16x16x32_bf16 v[34:37], v[154:157], v[178:181], v[34:37]
	v_mfma_f32_16x16x32_bf16 v[26:29], v[162:165], v[178:181], v[26:29]
	v_mfma_f32_16x16x32_bf16 v[18:21], v[154:157], v[186:189], v[18:21]
	v_mfma_f32_16x16x32_bf16 v[10:13], v[162:165], v[186:189], v[10:13]
	v_mfma_f32_16x16x32_bf16 v[6:9], v[154:157], v[202:205], v[6:9]
	v_mfma_f32_16x16x32_bf16 v[2:5], v[162:165], v[202:205], v[2:5]
	v_mfma_f32_16x16x32_bf16 v[50:53], v[158:161], v[174:177], v[50:53]
	v_mfma_f32_16x16x32_bf16 v[42:45], v[166:169], v[174:177], v[42:45]
	v_mfma_f32_16x16x32_bf16 v[34:37], v[158:161], v[182:185], v[34:37]
	v_mfma_f32_16x16x32_bf16 v[26:29], v[166:169], v[182:185], v[26:29]
	v_mfma_f32_16x16x32_bf16 v[18:21], v[158:161], v[190:193], v[18:21]
	v_mfma_f32_16x16x32_bf16 v[10:13], v[166:169], v[190:193], v[10:13]
	v_mfma_f32_16x16x32_bf16 v[6:9], v[158:161], v[206:209], v[6:9]
	v_mfma_f32_16x16x32_bf16 v[2:5], v[166:169], v[206:209], v[2:5]
	s_barrier
	s_setprio 0
	v_add_u32_e32 v150, s66, v136
	v_add_u32_e32 v166, s65, v136
	ds_read_b128 v[138:141], v150
	ds_read_b128 v[142:145], v150 offset:1024
	ds_read_b128 v[146:149], v150 offset:2048
	ds_read_b128 v[150:153], v150 offset:3072
	ds_read_b128 v[154:157], v166
	ds_read_b128 v[158:161], v166 offset:1024
	ds_read_b128 v[162:165], v166 offset:2048
	ds_read_b128 v[166:169], v166 offset:3072
	s_mov_b32 m0, s57
	v_lshl_add_u64 v[216:217], s[30:31], 0, v[132:133]
	ds_read_b128 v[170:173], v137 offset:32768
	ds_read_b128 v[174:177], v137 offset:33792
	ds_read_b128 v[178:181], v137 offset:34816
	ds_read_b128 v[182:185], v137 offset:35840
	ds_read_b128 v[186:189], v137 offset:36864
	ds_read_b128 v[190:193], v137 offset:37888
	ds_read_b128 v[202:205], v137 offset:38912
	ds_read_b128 v[206:209], v137 offset:39936
	global_load_lds_dwordx4 v[216:217], off
	v_lshl_add_u64 v[216:217], s[30:31], 0, v[130:131]
	s_mov_b32 m0, s58
	s_nop 0
	global_load_lds_dwordx4 v[216:217], off
	s_waitcnt vmcnt(8)
	s_waitcnt lgkmcnt(0)
	s_setprio 1
	s_barrier
	v_mfma_f32_16x16x32_bf16 v[126:129], v[138:141], v[170:173], v[126:129]
	v_mfma_f32_16x16x32_bf16 v[122:125], v[146:149], v[170:173], v[122:125]
	v_mfma_f32_16x16x32_bf16 v[118:121], v[138:141], v[178:181], v[118:121]
	v_mfma_f32_16x16x32_bf16 v[110:113], v[146:149], v[178:181], v[110:113]
	v_mfma_f32_16x16x32_bf16 v[102:105], v[138:141], v[186:189], v[102:105]
	v_mfma_f32_16x16x32_bf16 v[94:97], v[146:149], v[186:189], v[94:97]
	v_mfma_f32_16x16x32_bf16 v[86:89], v[138:141], v[202:205], v[86:89]
	v_mfma_f32_16x16x32_bf16 v[78:81], v[146:149], v[202:205], v[78:81]
	v_mfma_f32_16x16x32_bf16 v[126:129], v[142:145], v[174:177], v[126:129]
	v_mfma_f32_16x16x32_bf16 v[122:125], v[150:153], v[174:177], v[122:125]
	v_mfma_f32_16x16x32_bf16 v[118:121], v[142:145], v[182:185], v[118:121]
	v_mfma_f32_16x16x32_bf16 v[110:113], v[150:153], v[182:185], v[110:113]
	v_mfma_f32_16x16x32_bf16 v[102:105], v[142:145], v[190:193], v[102:105]
	v_mfma_f32_16x16x32_bf16 v[94:97], v[150:153], v[190:193], v[94:97]
	v_mfma_f32_16x16x32_bf16 v[86:89], v[142:145], v[206:209], v[86:89]
	v_mfma_f32_16x16x32_bf16 v[78:81], v[150:153], v[206:209], v[78:81]
	v_mfma_f32_16x16x32_bf16 v[114:117], v[154:157], v[170:173], v[114:117]
	v_mfma_f32_16x16x32_bf16 v[106:109], v[162:165], v[170:173], v[106:109]
	v_mfma_f32_16x16x32_bf16 v[98:101], v[154:157], v[178:181], v[98:101]
	v_mfma_f32_16x16x32_bf16 v[90:93], v[162:165], v[178:181], v[90:93]
	v_mfma_f32_16x16x32_bf16 v[82:85], v[154:157], v[186:189], v[82:85]
	v_mfma_f32_16x16x32_bf16 v[74:77], v[162:165], v[186:189], v[74:77]
	v_mfma_f32_16x16x32_bf16 v[70:73], v[154:157], v[202:205], v[70:73]
	v_mfma_f32_16x16x32_bf16 v[66:69], v[162:165], v[202:205], v[66:69]
	v_mfma_f32_16x16x32_bf16 v[114:117], v[158:161], v[174:177], v[114:117]
	v_mfma_f32_16x16x32_bf16 v[106:109], v[166:169], v[174:177], v[106:109]
	v_mfma_f32_16x16x32_bf16 v[98:101], v[158:161], v[182:185], v[98:101]
	v_mfma_f32_16x16x32_bf16 v[90:93], v[166:169], v[182:185], v[90:93]
	v_mfma_f32_16x16x32_bf16 v[82:85], v[158:161], v[190:193], v[82:85]
	v_mfma_f32_16x16x32_bf16 v[74:77], v[166:169], v[190:193], v[74:77]
	v_mfma_f32_16x16x32_bf16 v[70:73], v[158:161], v[206:209], v[70:73]
	v_mfma_f32_16x16x32_bf16 v[66:69], v[166:169], v[206:209], v[66:69]
	s_barrier
	s_setprio 0
	s_mov_b32 m0, s64
	v_lshl_add_u64 v[134:135], v[134:135], 0, s[10:11]
	ds_read_b128 v[170:173], v137 offset:49152
	ds_read_b128 v[174:177], v137 offset:50176
	ds_read_b128 v[178:181], v137 offset:51200
	ds_read_b128 v[182:185], v137 offset:52224
	ds_read_b128 v[186:189], v137 offset:53248
	ds_read_b128 v[190:193], v137 offset:54272
	ds_read_b128 v[202:205], v137 offset:55296
	ds_read_b128 v[206:209], v137 offset:56320
	global_load_lds_dwordx4 v[134:135], off
	v_lshl_add_u64 v[134:135], v[210:211], 0, s[10:11]
	s_mov_b32 m0, s21
	s_nop 0
	global_load_lds_dwordx4 v[134:135], off
	v_lshl_add_u64 v[134:135], s[28:29], 0, v[132:133]
	s_mov_b32 m0, s72
	s_nop 0
	global_load_lds_dwordx4 v[134:135], off
	v_lshl_add_u64 v[134:135], s[28:29], 0, v[130:131]
	s_mov_b32 m0, s71
	s_nop 0
	global_load_lds_dwordx4 v[134:135], off
	v_lshl_add_u64 v[134:135], v[212:213], 0, s[10:11]
	s_mov_b32 m0, s59
	s_nop 0
	global_load_lds_dwordx4 v[134:135], off
	v_lshl_add_u64 v[134:135], v[214:215], 0, s[10:11]
	s_mov_b32 m0, s60
	s_nop 0
	global_load_lds_dwordx4 v[134:135], off
	s_waitcnt vmcnt(8)
	s_waitcnt lgkmcnt(0)
	s_setprio 1
	s_barrier
	v_mfma_f32_16x16x32_bf16 v[62:65], v[138:141], v[170:173], v[62:65]
	v_mfma_f32_16x16x32_bf16 v[58:61], v[146:149], v[170:173], v[58:61]
	v_mfma_f32_16x16x32_bf16 v[54:57], v[138:141], v[178:181], v[54:57]
	v_mfma_f32_16x16x32_bf16 v[46:49], v[146:149], v[178:181], v[46:49]
	v_mfma_f32_16x16x32_bf16 v[38:41], v[138:141], v[186:189], v[38:41]
	v_mfma_f32_16x16x32_bf16 v[30:33], v[146:149], v[186:189], v[30:33]
	v_mfma_f32_16x16x32_bf16 v[22:25], v[138:141], v[202:205], v[22:25]
	v_mfma_f32_16x16x32_bf16 v[14:17], v[146:149], v[202:205], v[14:17]
	v_mfma_f32_16x16x32_bf16 v[62:65], v[142:145], v[174:177], v[62:65]
	v_mfma_f32_16x16x32_bf16 v[58:61], v[150:153], v[174:177], v[58:61]
	v_mfma_f32_16x16x32_bf16 v[54:57], v[142:145], v[182:185], v[54:57]
	v_mfma_f32_16x16x32_bf16 v[46:49], v[150:153], v[182:185], v[46:49]
	v_mfma_f32_16x16x32_bf16 v[38:41], v[142:145], v[190:193], v[38:41]
	v_mfma_f32_16x16x32_bf16 v[30:33], v[150:153], v[190:193], v[30:33]
	v_mfma_f32_16x16x32_bf16 v[22:25], v[142:145], v[206:209], v[22:25]
	v_mfma_f32_16x16x32_bf16 v[14:17], v[150:153], v[206:209], v[14:17]
	v_mfma_f32_16x16x32_bf16 v[50:53], v[154:157], v[170:173], v[50:53]
	v_mfma_f32_16x16x32_bf16 v[42:45], v[162:165], v[170:173], v[42:45]
	v_mfma_f32_16x16x32_bf16 v[34:37], v[154:157], v[178:181], v[34:37]
	v_mfma_f32_16x16x32_bf16 v[26:29], v[162:165], v[178:181], v[26:29]
	v_mfma_f32_16x16x32_bf16 v[18:21], v[154:157], v[186:189], v[18:21]
	v_mfma_f32_16x16x32_bf16 v[10:13], v[162:165], v[186:189], v[10:13]
	v_mfma_f32_16x16x32_bf16 v[6:9], v[154:157], v[202:205], v[6:9]
	v_mfma_f32_16x16x32_bf16 v[2:5], v[162:165], v[202:205], v[2:5]
	v_mfma_f32_16x16x32_bf16 v[50:53], v[158:161], v[174:177], v[50:53]
	v_mfma_f32_16x16x32_bf16 v[42:45], v[166:169], v[174:177], v[42:45]
	v_mfma_f32_16x16x32_bf16 v[34:37], v[158:161], v[182:185], v[34:37]
	v_mfma_f32_16x16x32_bf16 v[26:29], v[166:169], v[182:185], v[26:29]
	v_mfma_f32_16x16x32_bf16 v[18:21], v[158:161], v[190:193], v[18:21]
	v_mfma_f32_16x16x32_bf16 v[10:13], v[166:169], v[190:193], v[10:13]
	v_mfma_f32_16x16x32_bf16 v[6:9], v[158:161], v[206:209], v[6:9]
	v_mfma_f32_16x16x32_bf16 v[2:5], v[166:169], v[206:209], v[2:5]
	s_barrier
	s_setprio 0
	s_andn2_b64 vcc, exec, s[26:27]
	s_mov_b64 s[28:29], -1
	s_mov_b64 s[26:27], 0
	s_movk_i32 s21, 0x100
	s_cbranch_vccz .LBB0_1002
	s_and_b64 vcc, exec, s[16:17]
	s_cbranch_vccz .LBB0_1005
	s_barrier

.LBB0_1087:
	s_add_u32 s30, s28, 0xfff80080
	s_addc_u32 s31, s29, -1
	s_cmp_eq_u32 s83, 28
	s_cselect_b32 s43, s23, s31
	s_cselect_b32 s42, s44, s30
	s_cselect_b32 s31, s21, s82
	s_cselect_b32 s30, s45, s81
	s_add_i32 s84, 0, 0x10000
	s_add_i32 s86, 0, 0x14000
	v_add_u32_e32 v62, s84, v229
	v_add_u32_e32 v158, s86, v229
	ds_read_b128 v[42:45], v62
	ds_read_b128 v[46:49], v62 offset:1024
	ds_read_b128 v[58:61], v62 offset:2048
	ds_read_b128 v[62:65], v62 offset:3072
	ds_read_b128 v[146:149], v158
	ds_read_b128 v[150:153], v158 offset:1024
	ds_read_b128 v[154:157], v158 offset:2048
	ds_read_b128 v[158:161], v158 offset:3072
	v_lshl_add_u64 v[208:209], s[28:29], 0, v[204:205]
	s_add_i32 m0, s71, 0xc000
	ds_read_b128 v[162:165], v230
	ds_read_b128 v[166:169], v230 offset:1024
	ds_read_b128 v[170:173], v230 offset:2048
	ds_read_b128 v[174:177], v230 offset:3072
	ds_read_b128 v[178:181], v230 offset:4096
	ds_read_b128 v[182:185], v230 offset:5120
	ds_read_b128 v[186:189], v230 offset:6144
	ds_read_b128 v[190:193], v230 offset:7168
	global_load_lds_dwordx4 v[208:209], off
	v_lshl_add_u64 v[208:209], s[28:29], 0, v[206:207]
	s_add_i32 m0, s71, 0xe000
	s_nop 0
	global_load_lds_dwordx4 v[208:209], off
	s_waitcnt vmcnt(8)
	s_waitcnt lgkmcnt(0)
	s_setprio 1
	s_barrier
	v_mfma_f32_16x16x32_bf16 v[142:145], v[42:45], v[162:165], v[142:145]
	v_mfma_f32_16x16x32_bf16 v[138:141], v[58:61], v[162:165], v[138:141]
	v_mfma_f32_16x16x32_bf16 v[126:129], v[42:45], v[170:173], v[126:129]
	v_mfma_f32_16x16x32_bf16 v[122:125], v[58:61], v[170:173], v[122:125]
	v_mfma_f32_16x16x32_bf16 v[110:113], v[42:45], v[178:181], v[110:113]
	v_mfma_f32_16x16x32_bf16 v[106:109], v[58:61], v[178:181], v[106:109]
	v_mfma_f32_16x16x32_bf16 v[94:97], v[42:45], v[186:189], v[94:97]
	v_mfma_f32_16x16x32_bf16 v[90:93], v[58:61], v[186:189], v[90:93]
	v_mfma_f32_16x16x32_bf16 v[142:145], v[46:49], v[166:169], v[142:145]
	v_mfma_f32_16x16x32_bf16 v[138:141], v[62:65], v[166:169], v[138:141]
	v_mfma_f32_16x16x32_bf16 v[126:129], v[46:49], v[174:177], v[126:129]
	v_mfma_f32_16x16x32_bf16 v[122:125], v[62:65], v[174:177], v[122:125]
	v_mfma_f32_16x16x32_bf16 v[110:113], v[46:49], v[182:185], v[110:113]
	v_mfma_f32_16x16x32_bf16 v[106:109], v[62:65], v[182:185], v[106:109]
	v_mfma_f32_16x16x32_bf16 v[94:97], v[46:49], v[190:193], v[94:97]
	v_mfma_f32_16x16x32_bf16 v[90:93], v[62:65], v[190:193], v[90:93]
	v_mfma_f32_16x16x32_bf16 v[134:137], v[146:149], v[162:165], v[134:137]
	v_mfma_f32_16x16x32_bf16 v[130:133], v[154:157], v[162:165], v[130:133]
	v_mfma_f32_16x16x32_bf16 v[118:121], v[146:149], v[170:173], v[118:121]
	v_mfma_f32_16x16x32_bf16 v[114:117], v[154:157], v[170:173], v[114:117]
	v_mfma_f32_16x16x32_bf16 v[102:105], v[146:149], v[178:181], v[102:105]
	v_mfma_f32_16x16x32_bf16 v[98:101], v[154:157], v[178:181], v[98:101]
	v_mfma_f32_16x16x32_bf16 v[86:89], v[146:149], v[186:189], v[86:89]
	v_mfma_f32_16x16x32_bf16 v[82:85], v[154:157], v[186:189], v[82:85]
	v_mfma_f32_16x16x32_bf16 v[134:137], v[150:153], v[166:169], v[134:137]
	v_mfma_f32_16x16x32_bf16 v[130:133], v[158:161], v[166:169], v[130:133]
	v_mfma_f32_16x16x32_bf16 v[118:121], v[150:153], v[174:177], v[118:121]
	v_mfma_f32_16x16x32_bf16 v[114:117], v[158:161], v[174:177], v[114:117]
	v_mfma_f32_16x16x32_bf16 v[102:105], v[150:153], v[182:185], v[102:105]
	v_mfma_f32_16x16x32_bf16 v[98:101], v[158:161], v[182:185], v[98:101]
	v_mfma_f32_16x16x32_bf16 v[86:89], v[150:153], v[190:193], v[86:89]
	v_mfma_f32_16x16x32_bf16 v[82:85], v[158:161], v[190:193], v[82:85]
	s_barrier
	s_setprio 0
	s_add_i32 s84, s84, s70
	v_lshl_add_u64 v[208:209], s[30:31], 0, v[194:195]
	s_mov_b32 m0, s84
	ds_read_b128 v[162:165], v230 offset:16384
	ds_read_b128 v[166:169], v230 offset:17408
	ds_read_b128 v[170:173], v230 offset:18432
	ds_read_b128 v[174:177], v230 offset:19456
	ds_read_b128 v[178:181], v230 offset:20480
	ds_read_b128 v[182:185], v230 offset:21504
	ds_read_b128 v[186:189], v230 offset:22528
	ds_read_b128 v[190:193], v230 offset:23552
	global_load_lds_dwordx4 v[208:209], off
	s_add_i32 m0, s84, 0x2000
	s_add_u32 s84, s30, 0x80000
	v_lshl_add_u64 v[210:211], s[30:31], 0, v[202:203]
	s_addc_u32 s85, s31, 0
	s_add_i32 s86, s86, s70
	global_load_lds_dwordx4 v[210:211], off
	v_lshl_add_u64 v[212:213], s[84:85], 0, v[194:195]
	s_mov_b32 m0, s86
	v_lshl_add_u64 v[214:215], s[42:43], 0, v[202:203]
	global_load_lds_dwordx4 v[212:213], off
	v_lshl_add_u64 v[212:213], s[84:85], 0, v[202:203]
	s_add_i32 m0, s86, 0x2000
	s_nop 0
	global_load_lds_dwordx4 v[212:213], off
	v_lshl_add_u64 v[212:213], s[42:43], 0, v[194:195]
	s_mov_b32 m0, s71
	s_nop 0
	global_load_lds_dwordx4 v[212:213], off
	s_mov_b32 m0, s72
	s_nop 0
	global_load_lds_dwordx4 v[214:215], off
	s_waitcnt vmcnt(8)
	s_waitcnt lgkmcnt(0)
	s_setprio 1
	s_barrier
	v_mfma_f32_16x16x32_bf16 v[78:81], v[42:45], v[162:165], v[78:81]
	v_mfma_f32_16x16x32_bf16 v[74:77], v[58:61], v[162:165], v[74:77]
	v_mfma_f32_16x16x32_bf16 v[54:57], v[42:45], v[170:173], v[54:57]
	v_mfma_f32_16x16x32_bf16 v[50:53], v[58:61], v[170:173], v[50:53]
	v_mfma_f32_16x16x32_bf16 v[30:33], v[42:45], v[178:181], v[30:33]
	v_mfma_f32_16x16x32_bf16 v[26:29], v[58:61], v[178:181], v[26:29]
	v_mfma_f32_16x16x32_bf16 v[14:17], v[42:45], v[186:189], v[14:17]
	v_mfma_f32_16x16x32_bf16 v[10:13], v[58:61], v[186:189], v[10:13]
	v_mfma_f32_16x16x32_bf16 v[78:81], v[46:49], v[166:169], v[78:81]
	v_mfma_f32_16x16x32_bf16 v[74:77], v[62:65], v[166:169], v[74:77]
	v_mfma_f32_16x16x32_bf16 v[54:57], v[46:49], v[174:177], v[54:57]
	v_mfma_f32_16x16x32_bf16 v[50:53], v[62:65], v[174:177], v[50:53]
	v_mfma_f32_16x16x32_bf16 v[30:33], v[46:49], v[182:185], v[30:33]
	v_mfma_f32_16x16x32_bf16 v[26:29], v[62:65], v[182:185], v[26:29]
	v_mfma_f32_16x16x32_bf16 v[14:17], v[46:49], v[190:193], v[14:17]
	v_mfma_f32_16x16x32_bf16 v[10:13], v[62:65], v[190:193], v[10:13]
	v_mfma_f32_16x16x32_bf16 v[38:41], v[146:149], v[170:173], v[38:41]
	v_mfma_f32_16x16x32_bf16 v[34:37], v[154:157], v[170:173], v[34:37]
	v_mfma_f32_16x16x32_bf16 v[22:25], v[146:149], v[178:181], v[22:25]
	v_mfma_f32_16x16x32_bf16 v[18:21], v[154:157], v[178:181], v[18:21]
	v_mfma_f32_16x16x32_bf16 v[6:9], v[146:149], v[186:189], v[6:9]
	v_mfma_f32_16x16x32_bf16 v[2:5], v[154:157], v[186:189], v[2:5]
	v_mfma_f32_16x16x32_bf16 v[42:45], v[146:149], v[162:165], v[70:73]
	v_mfma_f32_16x16x32_bf16 v[46:49], v[154:157], v[162:165], v[66:69]
	v_mfma_f32_16x16x32_bf16 v[38:41], v[150:153], v[174:177], v[38:41]
	v_mfma_f32_16x16x32_bf16 v[34:37], v[158:161], v[174:177], v[34:37]
	v_mfma_f32_16x16x32_bf16 v[22:25], v[150:153], v[182:185], v[22:25]
	v_mfma_f32_16x16x32_bf16 v[18:21], v[158:161], v[182:185], v[18:21]
	v_mfma_f32_16x16x32_bf16 v[6:9], v[150:153], v[190:193], v[6:9]
	v_mfma_f32_16x16x32_bf16 v[2:5], v[158:161], v[190:193], v[2:5]
	v_mfma_f32_16x16x32_bf16 v[42:45], v[150:153], v[166:169], v[42:45]
	v_mfma_f32_16x16x32_bf16 v[46:49], v[158:161], v[166:169], v[46:49]
	s_barrier
	s_setprio 0
	s_add_i32 s84, 0, 0x18000
	s_add_i32 s85, 0, 0x1c000
	v_add_u32_e32 v70, s84, v229
	v_add_u32_e32 v158, s85, v229
	ds_read_b128 v[58:61], v70
	ds_read_b128 v[62:65], v70 offset:1024
	ds_read_b128 v[66:69], v70 offset:2048
	ds_read_b128 v[70:73], v70 offset:3072
	ds_read_b128 v[146:149], v158
	ds_read_b128 v[150:153], v158 offset:1024
	ds_read_b128 v[154:157], v158 offset:2048
	ds_read_b128 v[158:161], v158 offset:3072
	s_add_u32 s42, s42, 0x80000
	s_addc_u32 s43, s43, 0
	s_mov_b32 m0, s73
	v_lshl_add_u64 v[216:217], s[42:43], 0, v[194:195]
	ds_read_b128 v[162:165], v230 offset:32768
	ds_read_b128 v[166:169], v230 offset:33792
	ds_read_b128 v[170:173], v230 offset:34816
	ds_read_b128 v[174:177], v230 offset:35840
	ds_read_b128 v[178:181], v230 offset:36864
	ds_read_b128 v[182:185], v230 offset:37888
	ds_read_b128 v[186:189], v230 offset:38912
	ds_read_b128 v[190:193], v230 offset:39936
	global_load_lds_dwordx4 v[216:217], off
	v_lshl_add_u64 v[216:217], s[42:43], 0, v[202:203]
	s_mov_b32 m0, s74
	s_nop 0
	global_load_lds_dwordx4 v[216:217], off
	s_waitcnt vmcnt(8)
	s_waitcnt lgkmcnt(0)
	s_setprio 1
	s_barrier
	v_mfma_f32_16x16x32_bf16 v[142:145], v[58:61], v[162:165], v[142:145]
	v_mfma_f32_16x16x32_bf16 v[138:141], v[66:69], v[162:165], v[138:141]
	v_mfma_f32_16x16x32_bf16 v[126:129], v[58:61], v[170:173], v[126:129]
	v_mfma_f32_16x16x32_bf16 v[122:125], v[66:69], v[170:173], v[122:125]
	v_mfma_f32_16x16x32_bf16 v[110:113], v[58:61], v[178:181], v[110:113]
	v_mfma_f32_16x16x32_bf16 v[106:109], v[66:69], v[178:181], v[106:109]
	v_mfma_f32_16x16x32_bf16 v[94:97], v[58:61], v[186:189], v[94:97]
	v_mfma_f32_16x16x32_bf16 v[90:93], v[66:69], v[186:189], v[90:93]
	v_mfma_f32_16x16x32_bf16 v[142:145], v[62:65], v[166:169], v[142:145]
	v_mfma_f32_16x16x32_bf16 v[138:141], v[70:73], v[166:169], v[138:141]
	v_mfma_f32_16x16x32_bf16 v[126:129], v[62:65], v[174:177], v[126:129]
	v_mfma_f32_16x16x32_bf16 v[122:125], v[70:73], v[174:177], v[122:125]
	v_mfma_f32_16x16x32_bf16 v[110:113], v[62:65], v[182:185], v[110:113]
	v_mfma_f32_16x16x32_bf16 v[106:109], v[70:73], v[182:185], v[106:109]
	v_mfma_f32_16x16x32_bf16 v[94:97], v[62:65], v[190:193], v[94:97]
	v_mfma_f32_16x16x32_bf16 v[90:93], v[70:73], v[190:193], v[90:93]
	v_mfma_f32_16x16x32_bf16 v[134:137], v[146:149], v[162:165], v[134:137]
	v_mfma_f32_16x16x32_bf16 v[130:133], v[154:157], v[162:165], v[130:133]
	v_mfma_f32_16x16x32_bf16 v[118:121], v[146:149], v[170:173], v[118:121]
	v_mfma_f32_16x16x32_bf16 v[114:117], v[154:157], v[170:173], v[114:117]
	v_mfma_f32_16x16x32_bf16 v[102:105], v[146:149], v[178:181], v[102:105]
	v_mfma_f32_16x16x32_bf16 v[98:101], v[154:157], v[178:181], v[98:101]
	v_mfma_f32_16x16x32_bf16 v[86:89], v[146:149], v[186:189], v[86:89]
	v_mfma_f32_16x16x32_bf16 v[82:85], v[154:157], v[186:189], v[82:85]
	v_mfma_f32_16x16x32_bf16 v[134:137], v[150:153], v[166:169], v[134:137]
	v_mfma_f32_16x16x32_bf16 v[130:133], v[158:161], v[166:169], v[130:133]
	v_mfma_f32_16x16x32_bf16 v[118:121], v[150:153], v[174:177], v[118:121]
	v_mfma_f32_16x16x32_bf16 v[114:117], v[158:161], v[174:177], v[114:117]
	v_mfma_f32_16x16x32_bf16 v[102:105], v[150:153], v[182:185], v[102:105]
	v_mfma_f32_16x16x32_bf16 v[98:101], v[158:161], v[182:185], v[98:101]
	v_mfma_f32_16x16x32_bf16 v[86:89], v[150:153], v[190:193], v[86:89]
	v_mfma_f32_16x16x32_bf16 v[82:85], v[158:161], v[190:193], v[82:85]
	s_barrier
	s_setprio 0
	s_add_i32 s42, s84, s70
	v_lshl_add_u64 v[208:209], v[208:209], 0, s[10:11]
	s_mov_b32 m0, s42
	ds_read_b128 v[162:165], v230 offset:49152
	ds_read_b128 v[166:169], v230 offset:50176
	ds_read_b128 v[170:173], v230 offset:51200
	ds_read_b128 v[174:177], v230 offset:52224
	ds_read_b128 v[178:181], v230 offset:53248
	ds_read_b128 v[182:185], v230 offset:54272
	ds_read_b128 v[186:189], v230 offset:55296
	ds_read_b128 v[190:193], v230 offset:56320
	global_load_lds_dwordx4 v[208:209], off
	s_add_i32 m0, s42, 0x2000
	s_add_u32 s30, s30, 0x80080
	v_lshl_add_u64 v[208:209], v[210:211], 0, s[10:11]
	s_addc_u32 s31, s31, 0
	s_add_i32 s42, s85, s70
	global_load_lds_dwordx4 v[208:209], off
	v_lshl_add_u64 v[208:209], s[30:31], 0, v[194:195]
	s_mov_b32 m0, s42
	s_nop 0
	global_load_lds_dwordx4 v[208:209], off
	v_lshl_add_u64 v[208:209], s[30:31], 0, v[202:203]
	s_add_i32 m0, s42, 0x2000
	s_nop 0
	global_load_lds_dwordx4 v[208:209], off
	v_lshl_add_u64 v[208:209], v[212:213], 0, s[10:11]
	s_mov_b32 m0, s79
	s_nop 0
	global_load_lds_dwordx4 v[208:209], off
	v_lshl_add_u64 v[208:209], v[214:215], 0, s[10:11]
	s_mov_b32 m0, s80
	s_nop 0
	global_load_lds_dwordx4 v[208:209], off
	s_waitcnt vmcnt(8)
	s_waitcnt lgkmcnt(0)
	s_setprio 1
	s_barrier
	v_mfma_f32_16x16x32_bf16 v[78:81], v[58:61], v[162:165], v[78:81]
	v_mfma_f32_16x16x32_bf16 v[74:77], v[66:69], v[162:165], v[74:77]
	v_mfma_f32_16x16x32_bf16 v[54:57], v[58:61], v[170:173], v[54:57]
	v_mfma_f32_16x16x32_bf16 v[50:53], v[66:69], v[170:173], v[50:53]
	v_mfma_f32_16x16x32_bf16 v[30:33], v[58:61], v[178:181], v[30:33]
	v_mfma_f32_16x16x32_bf16 v[26:29], v[66:69], v[178:181], v[26:29]
	v_mfma_f32_16x16x32_bf16 v[14:17], v[58:61], v[186:189], v[14:17]
	v_mfma_f32_16x16x32_bf16 v[10:13], v[66:69], v[186:189], v[10:13]
	v_mfma_f32_16x16x32_bf16 v[78:81], v[62:65], v[166:169], v[78:81]
	v_mfma_f32_16x16x32_bf16 v[74:77], v[70:73], v[166:169], v[74:77]
	v_mfma_f32_16x16x32_bf16 v[54:57], v[62:65], v[174:177], v[54:57]
	v_mfma_f32_16x16x32_bf16 v[50:53], v[70:73], v[174:177], v[50:53]
	v_mfma_f32_16x16x32_bf16 v[30:33], v[62:65], v[182:185], v[30:33]
	v_mfma_f32_16x16x32_bf16 v[26:29], v[70:73], v[182:185], v[26:29]
	v_mfma_f32_16x16x32_bf16 v[14:17], v[62:65], v[190:193], v[14:17]
	v_mfma_f32_16x16x32_bf16 v[10:13], v[70:73], v[190:193], v[10:13]
	v_mfma_f32_16x16x32_bf16 v[42:45], v[146:149], v[162:165], v[42:45]
	v_mfma_f32_16x16x32_bf16 v[70:73], v[150:153], v[166:169], v[42:45]
	v_mfma_f32_16x16x32_bf16 v[42:45], v[154:157], v[162:165], v[46:49]
	v_mfma_f32_16x16x32_bf16 v[38:41], v[146:149], v[170:173], v[38:41]
	v_mfma_f32_16x16x32_bf16 v[34:37], v[154:157], v[170:173], v[34:37]
	v_mfma_f32_16x16x32_bf16 v[22:25], v[146:149], v[178:181], v[22:25]
	v_mfma_f32_16x16x32_bf16 v[18:21], v[154:157], v[178:181], v[18:21]
	v_mfma_f32_16x16x32_bf16 v[6:9], v[146:149], v[186:189], v[6:9]
	v_mfma_f32_16x16x32_bf16 v[2:5], v[154:157], v[186:189], v[2:5]
	v_mfma_f32_16x16x32_bf16 v[66:69], v[158:161], v[166:169], v[42:45]
	v_mfma_f32_16x16x32_bf16 v[38:41], v[150:153], v[174:177], v[38:41]
	v_mfma_f32_16x16x32_bf16 v[34:37], v[158:161], v[174:177], v[34:37]
	v_mfma_f32_16x16x32_bf16 v[22:25], v[150:153], v[182:185], v[22:25]
	v_mfma_f32_16x16x32_bf16 v[18:21], v[158:161], v[182:185], v[18:21]
	v_mfma_f32_16x16x32_bf16 v[6:9], v[150:153], v[190:193], v[6:9]
	v_mfma_f32_16x16x32_bf16 v[2:5], v[158:161], v[190:193], v[2:5]
	s_barrier
	s_setprio 0
	s_add_i32 s83, s83, 2
	s_add_u32 s28, s28, 0x100
	s_addc_u32 s29, s29, 0
	s_add_u32 s81, s81, 0x100
	s_addc_u32 s82, s82, 0
	s_cmp_gt_u32 s83, 29
	s_cbranch_scc0 .LBB0_1087
	s_and_b64 vcc, exec, s[16:17]
	s_cbranch_vccz .LBB0_1090
	s_barrier

.LBB0_1272:
	s_add_u32 s30, s28, 0xfff80080
	s_addc_u32 s31, s29, -1
	s_add_i32 s66, 0, 0x10000
	s_cmp_eq_u32 s65, 28
	s_cselect_b32 s37, s60, s31
	s_cselect_b32 s36, s61, s30
	s_cselect_b32 s31, s21, s64
	s_cselect_b32 s30, s62, s63
	s_add_i32 s68, 0, 0x14000
	v_add_u32_e32 v126, s66, v156
	v_add_u32_e32 v154, s68, v156
	ds_read_b128 v[114:117], v126
	ds_read_b128 v[118:121], v126 offset:1024
	ds_read_b128 v[122:125], v126 offset:2048
	ds_read_b128 v[126:129], v126 offset:3072
	ds_read_b128 v[158:161], v154
	ds_read_b128 v[162:165], v154 offset:1024
	ds_read_b128 v[166:169], v154 offset:2048
	ds_read_b128 v[170:173], v154 offset:3072
	v_lshl_add_u64 v[154:155], s[28:29], 0, v[150:151]
	s_add_i32 m0, s49, 0xc000
	ds_read_b128 v[174:177], v157
	ds_read_b128 v[178:181], v157 offset:1024
	ds_read_b128 v[182:185], v157 offset:2048
	ds_read_b128 v[186:189], v157 offset:3072
	ds_read_b128 v[190:193], v157 offset:4096
	ds_read_b128 v[202:205], v157 offset:5120
	ds_read_b128 v[206:209], v157 offset:6144
	ds_read_b128 v[210:213], v157 offset:7168
	global_load_lds_dwordx4 v[154:155], off
	v_lshl_add_u64 v[154:155], s[28:29], 0, v[152:153]
	s_add_i32 m0, s49, 0xe000
	s_nop 0
	global_load_lds_dwordx4 v[154:155], off
	s_waitcnt vmcnt(8)
	s_waitcnt lgkmcnt(0)
	s_setprio 1
	s_barrier
	v_mfma_f32_16x16x32_bf16 v[142:145], v[114:117], v[174:177], v[142:145]
	v_mfma_f32_16x16x32_bf16 v[138:141], v[122:125], v[174:177], v[138:141]
	v_mfma_f32_16x16x32_bf16 v[110:113], v[114:117], v[182:185], v[110:113]
	v_mfma_f32_16x16x32_bf16 v[106:109], v[122:125], v[182:185], v[106:109]
	v_mfma_f32_16x16x32_bf16 v[94:97], v[114:117], v[190:193], v[94:97]
	v_mfma_f32_16x16x32_bf16 v[90:93], v[122:125], v[190:193], v[90:93]
	v_mfma_f32_16x16x32_bf16 v[78:81], v[114:117], v[206:209], v[78:81]
	v_mfma_f32_16x16x32_bf16 v[74:77], v[122:125], v[206:209], v[74:77]
	v_mfma_f32_16x16x32_bf16 v[142:145], v[118:121], v[178:181], v[142:145]
	v_mfma_f32_16x16x32_bf16 v[138:141], v[126:129], v[178:181], v[138:141]
	v_mfma_f32_16x16x32_bf16 v[110:113], v[118:121], v[186:189], v[110:113]
	v_mfma_f32_16x16x32_bf16 v[106:109], v[126:129], v[186:189], v[106:109]
	v_mfma_f32_16x16x32_bf16 v[94:97], v[118:121], v[202:205], v[94:97]
	v_mfma_f32_16x16x32_bf16 v[90:93], v[126:129], v[202:205], v[90:93]
	v_mfma_f32_16x16x32_bf16 v[78:81], v[118:121], v[210:213], v[78:81]
	v_mfma_f32_16x16x32_bf16 v[74:77], v[126:129], v[210:213], v[74:77]
	v_mfma_f32_16x16x32_bf16 v[134:137], v[158:161], v[174:177], v[134:137]
	v_mfma_f32_16x16x32_bf16 v[130:133], v[166:169], v[174:177], v[130:133]
	v_mfma_f32_16x16x32_bf16 v[102:105], v[158:161], v[182:185], v[102:105]
	v_mfma_f32_16x16x32_bf16 v[98:101], v[166:169], v[182:185], v[98:101]
	v_mfma_f32_16x16x32_bf16 v[86:89], v[158:161], v[190:193], v[86:89]
	v_mfma_f32_16x16x32_bf16 v[82:85], v[166:169], v[190:193], v[82:85]
	v_mfma_f32_16x16x32_bf16 v[70:73], v[158:161], v[206:209], v[70:73]
	v_mfma_f32_16x16x32_bf16 v[66:69], v[166:169], v[206:209], v[66:69]
	v_mfma_f32_16x16x32_bf16 v[134:137], v[162:165], v[178:181], v[134:137]
	v_mfma_f32_16x16x32_bf16 v[130:133], v[170:173], v[178:181], v[130:133]
	v_mfma_f32_16x16x32_bf16 v[102:105], v[162:165], v[186:189], v[102:105]
	v_mfma_f32_16x16x32_bf16 v[98:101], v[170:173], v[186:189], v[98:101]
	v_mfma_f32_16x16x32_bf16 v[86:89], v[162:165], v[202:205], v[86:89]
	v_mfma_f32_16x16x32_bf16 v[82:85], v[170:173], v[202:205], v[82:85]
	v_mfma_f32_16x16x32_bf16 v[70:73], v[162:165], v[210:213], v[70:73]
	v_mfma_f32_16x16x32_bf16 v[66:69], v[170:173], v[210:213], v[66:69]
	s_barrier
	s_setprio 0
	s_add_i32 s66, s66, s48
	v_lshl_add_u64 v[154:155], s[30:31], 0, v[146:147]
	s_mov_b32 m0, s66
	ds_read_b128 v[174:177], v157 offset:16384
	ds_read_b128 v[178:181], v157 offset:17408
	ds_read_b128 v[182:185], v157 offset:18432
	ds_read_b128 v[186:189], v157 offset:19456
	ds_read_b128 v[190:193], v157 offset:20480
	ds_read_b128 v[202:205], v157 offset:21504
	ds_read_b128 v[206:209], v157 offset:22528
	ds_read_b128 v[210:213], v157 offset:23552
	global_load_lds_dwordx4 v[154:155], off
	s_add_i32 m0, s66, 0x2000
	s_add_u32 s66, s30, 0x80000
	v_lshl_add_u64 v[214:215], s[30:31], 0, v[148:149]
	s_addc_u32 s67, s31, 0
	s_add_i32 s68, s68, s48
	global_load_lds_dwordx4 v[214:215], off
	v_lshl_add_u64 v[216:217], s[66:67], 0, v[146:147]
	s_mov_b32 m0, s68
	v_lshl_add_u64 v[228:229], s[36:37], 0, v[148:149]
	global_load_lds_dwordx4 v[216:217], off
	v_lshl_add_u64 v[216:217], s[66:67], 0, v[148:149]
	s_add_i32 m0, s68, 0x2000
	s_nop 0
	global_load_lds_dwordx4 v[216:217], off
	v_lshl_add_u64 v[216:217], s[36:37], 0, v[146:147]
	s_mov_b32 m0, s49
	s_nop 0
	global_load_lds_dwordx4 v[216:217], off
	s_mov_b32 m0, s50
	s_nop 0
	global_load_lds_dwordx4 v[228:229], off
	s_waitcnt vmcnt(8)
	s_waitcnt lgkmcnt(0)
	s_setprio 1
	s_barrier
	v_mfma_f32_16x16x32_bf16 v[62:65], v[114:117], v[174:177], v[62:65]
	v_mfma_f32_16x16x32_bf16 v[58:61], v[122:125], v[174:177], v[58:61]
	v_mfma_f32_16x16x32_bf16 v[46:49], v[114:117], v[182:185], v[46:49]
	v_mfma_f32_16x16x32_bf16 v[42:45], v[122:125], v[182:185], v[42:45]
	v_mfma_f32_16x16x32_bf16 v[30:33], v[114:117], v[190:193], v[30:33]
	v_mfma_f32_16x16x32_bf16 v[26:29], v[122:125], v[190:193], v[26:29]
	v_mfma_f32_16x16x32_bf16 v[14:17], v[114:117], v[206:209], v[14:17]
	v_mfma_f32_16x16x32_bf16 v[10:13], v[122:125], v[206:209], v[10:13]
	v_mfma_f32_16x16x32_bf16 v[62:65], v[118:121], v[178:181], v[62:65]
	v_mfma_f32_16x16x32_bf16 v[58:61], v[126:129], v[178:181], v[58:61]
	v_mfma_f32_16x16x32_bf16 v[46:49], v[118:121], v[186:189], v[46:49]
	v_mfma_f32_16x16x32_bf16 v[42:45], v[126:129], v[186:189], v[42:45]
	v_mfma_f32_16x16x32_bf16 v[30:33], v[118:121], v[202:205], v[30:33]
	v_mfma_f32_16x16x32_bf16 v[26:29], v[126:129], v[202:205], v[26:29]
	v_mfma_f32_16x16x32_bf16 v[14:17], v[118:121], v[210:213], v[14:17]
	v_mfma_f32_16x16x32_bf16 v[10:13], v[126:129], v[210:213], v[10:13]
	v_mfma_f32_16x16x32_bf16 v[54:57], v[158:161], v[174:177], v[54:57]
	v_mfma_f32_16x16x32_bf16 v[50:53], v[166:169], v[174:177], v[50:53]
	v_mfma_f32_16x16x32_bf16 v[38:41], v[158:161], v[182:185], v[38:41]
	v_mfma_f32_16x16x32_bf16 v[34:37], v[166:169], v[182:185], v[34:37]
	v_mfma_f32_16x16x32_bf16 v[22:25], v[158:161], v[190:193], v[22:25]
	v_mfma_f32_16x16x32_bf16 v[18:21], v[166:169], v[190:193], v[18:21]
	v_mfma_f32_16x16x32_bf16 v[6:9], v[158:161], v[206:209], v[6:9]
	v_mfma_f32_16x16x32_bf16 v[2:5], v[166:169], v[206:209], v[2:5]
	v_mfma_f32_16x16x32_bf16 v[54:57], v[162:165], v[178:181], v[54:57]
	v_mfma_f32_16x16x32_bf16 v[50:53], v[170:173], v[178:181], v[50:53]
	v_mfma_f32_16x16x32_bf16 v[38:41], v[162:165], v[186:189], v[38:41]
	v_mfma_f32_16x16x32_bf16 v[34:37], v[170:173], v[186:189], v[34:37]
	v_mfma_f32_16x16x32_bf16 v[22:25], v[162:165], v[202:205], v[22:25]
	v_mfma_f32_16x16x32_bf16 v[18:21], v[170:173], v[202:205], v[18:21]
	v_mfma_f32_16x16x32_bf16 v[6:9], v[162:165], v[210:213], v[6:9]
	v_mfma_f32_16x16x32_bf16 v[2:5], v[170:173], v[210:213], v[2:5]
	s_barrier
	s_setprio 0
	s_add_i32 s66, 0, 0x18000
	s_add_i32 s67, 0, 0x1c000
	v_add_u32_e32 v126, s66, v156
	v_add_u32_e32 v170, s67, v156
	ds_read_b128 v[114:117], v126
	ds_read_b128 v[118:121], v126 offset:1024
	ds_read_b128 v[122:125], v126 offset:2048
	ds_read_b128 v[126:129], v126 offset:3072
	ds_read_b128 v[158:161], v170
	ds_read_b128 v[162:165], v170 offset:1024
	ds_read_b128 v[166:169], v170 offset:2048
	ds_read_b128 v[170:173], v170 offset:3072
	s_add_u32 s36, s36, 0x80000
	s_addc_u32 s37, s37, 0
	s_mov_b32 m0, s51
	v_lshl_add_u64 v[230:231], s[36:37], 0, v[146:147]
	ds_read_b128 v[174:177], v157 offset:32768
	ds_read_b128 v[178:181], v157 offset:33792
	ds_read_b128 v[182:185], v157 offset:34816
	ds_read_b128 v[186:189], v157 offset:35840
	ds_read_b128 v[190:193], v157 offset:36864
	ds_read_b128 v[202:205], v157 offset:37888
	ds_read_b128 v[206:209], v157 offset:38912
	ds_read_b128 v[210:213], v157 offset:39936
	global_load_lds_dwordx4 v[230:231], off
	v_lshl_add_u64 v[230:231], s[36:37], 0, v[148:149]
	s_mov_b32 m0, s52
	s_nop 0
	global_load_lds_dwordx4 v[230:231], off
	s_waitcnt vmcnt(8)
	s_waitcnt lgkmcnt(0)
	s_setprio 1
	s_barrier
	v_mfma_f32_16x16x32_bf16 v[142:145], v[114:117], v[174:177], v[142:145]
	v_mfma_f32_16x16x32_bf16 v[138:141], v[122:125], v[174:177], v[138:141]
	v_mfma_f32_16x16x32_bf16 v[110:113], v[114:117], v[182:185], v[110:113]
	v_mfma_f32_16x16x32_bf16 v[106:109], v[122:125], v[182:185], v[106:109]
	v_mfma_f32_16x16x32_bf16 v[94:97], v[114:117], v[190:193], v[94:97]
	v_mfma_f32_16x16x32_bf16 v[90:93], v[122:125], v[190:193], v[90:93]
	v_mfma_f32_16x16x32_bf16 v[78:81], v[114:117], v[206:209], v[78:81]
	v_mfma_f32_16x16x32_bf16 v[74:77], v[122:125], v[206:209], v[74:77]
	v_mfma_f32_16x16x32_bf16 v[142:145], v[118:121], v[178:181], v[142:145]
	v_mfma_f32_16x16x32_bf16 v[138:141], v[126:129], v[178:181], v[138:141]
	v_mfma_f32_16x16x32_bf16 v[110:113], v[118:121], v[186:189], v[110:113]
	v_mfma_f32_16x16x32_bf16 v[106:109], v[126:129], v[186:189], v[106:109]
	v_mfma_f32_16x16x32_bf16 v[94:97], v[118:121], v[202:205], v[94:97]
	v_mfma_f32_16x16x32_bf16 v[90:93], v[126:129], v[202:205], v[90:93]
	v_mfma_f32_16x16x32_bf16 v[78:81], v[118:121], v[210:213], v[78:81]
	v_mfma_f32_16x16x32_bf16 v[74:77], v[126:129], v[210:213], v[74:77]
	v_mfma_f32_16x16x32_bf16 v[134:137], v[158:161], v[174:177], v[134:137]
	v_mfma_f32_16x16x32_bf16 v[130:133], v[166:169], v[174:177], v[130:133]
	v_mfma_f32_16x16x32_bf16 v[102:105], v[158:161], v[182:185], v[102:105]
	v_mfma_f32_16x16x32_bf16 v[98:101], v[166:169], v[182:185], v[98:101]
	v_mfma_f32_16x16x32_bf16 v[86:89], v[158:161], v[190:193], v[86:89]
	v_mfma_f32_16x16x32_bf16 v[82:85], v[166:169], v[190:193], v[82:85]
	v_mfma_f32_16x16x32_bf16 v[70:73], v[158:161], v[206:209], v[70:73]
	v_mfma_f32_16x16x32_bf16 v[66:69], v[166:169], v[206:209], v[66:69]
	v_mfma_f32_16x16x32_bf16 v[134:137], v[162:165], v[178:181], v[134:137]
	v_mfma_f32_16x16x32_bf16 v[130:133], v[170:173], v[178:181], v[130:133]
	v_mfma_f32_16x16x32_bf16 v[102:105], v[162:165], v[186:189], v[102:105]
	v_mfma_f32_16x16x32_bf16 v[98:101], v[170:173], v[186:189], v[98:101]
	v_mfma_f32_16x16x32_bf16 v[86:89], v[162:165], v[202:205], v[86:89]
	v_mfma_f32_16x16x32_bf16 v[82:85], v[170:173], v[202:205], v[82:85]
	v_mfma_f32_16x16x32_bf16 v[70:73], v[162:165], v[210:213], v[70:73]
	v_mfma_f32_16x16x32_bf16 v[66:69], v[170:173], v[210:213], v[66:69]
	s_barrier
	s_setprio 0
	s_add_i32 s36, s66, s48
	v_lshl_add_u64 v[154:155], v[154:155], 0, s[10:11]
	s_mov_b32 m0, s36
	ds_read_b128 v[174:177], v157 offset:49152
	ds_read_b128 v[178:181], v157 offset:50176
	ds_read_b128 v[182:185], v157 offset:51200
	ds_read_b128 v[186:189], v157 offset:52224
	ds_read_b128 v[190:193], v157 offset:53248
	ds_read_b128 v[202:205], v157 offset:54272
	ds_read_b128 v[206:209], v157 offset:55296
	ds_read_b128 v[210:213], v157 offset:56320
	global_load_lds_dwordx4 v[154:155], off
	s_add_i32 m0, s36, 0x2000
	s_add_u32 s30, s30, 0x80080
	v_lshl_add_u64 v[154:155], v[214:215], 0, s[10:11]
	s_addc_u32 s31, s31, 0
	s_add_i32 s36, s67, s48
	global_load_lds_dwordx4 v[154:155], off
	v_lshl_add_u64 v[154:155], s[30:31], 0, v[146:147]
	s_mov_b32 m0, s36
	s_nop 0
	global_load_lds_dwordx4 v[154:155], off
	v_lshl_add_u64 v[154:155], s[30:31], 0, v[148:149]
	s_add_i32 m0, s36, 0x2000
	s_nop 0
	global_load_lds_dwordx4 v[154:155], off
	v_lshl_add_u64 v[154:155], v[216:217], 0, s[10:11]
	s_mov_b32 m0, s53
	s_nop 0
	global_load_lds_dwordx4 v[154:155], off
	v_lshl_add_u64 v[154:155], v[228:229], 0, s[10:11]
	s_mov_b32 m0, s56
	s_nop 0
	global_load_lds_dwordx4 v[154:155], off
	s_waitcnt vmcnt(8)
	s_waitcnt lgkmcnt(0)
	s_setprio 1
	s_barrier
	v_mfma_f32_16x16x32_bf16 v[62:65], v[114:117], v[174:177], v[62:65]
	v_mfma_f32_16x16x32_bf16 v[58:61], v[122:125], v[174:177], v[58:61]
	v_mfma_f32_16x16x32_bf16 v[46:49], v[114:117], v[182:185], v[46:49]
	v_mfma_f32_16x16x32_bf16 v[42:45], v[122:125], v[182:185], v[42:45]
	v_mfma_f32_16x16x32_bf16 v[30:33], v[114:117], v[190:193], v[30:33]
	v_mfma_f32_16x16x32_bf16 v[26:29], v[122:125], v[190:193], v[26:29]
	v_mfma_f32_16x16x32_bf16 v[14:17], v[114:117], v[206:209], v[14:17]
	v_mfma_f32_16x16x32_bf16 v[10:13], v[122:125], v[206:209], v[10:13]
	v_mfma_f32_16x16x32_bf16 v[62:65], v[118:121], v[178:181], v[62:65]
	v_mfma_f32_16x16x32_bf16 v[58:61], v[126:129], v[178:181], v[58:61]
	v_mfma_f32_16x16x32_bf16 v[46:49], v[118:121], v[186:189], v[46:49]
	v_mfma_f32_16x16x32_bf16 v[42:45], v[126:129], v[186:189], v[42:45]
	v_mfma_f32_16x16x32_bf16 v[30:33], v[118:121], v[202:205], v[30:33]
	v_mfma_f32_16x16x32_bf16 v[26:29], v[126:129], v[202:205], v[26:29]
	v_mfma_f32_16x16x32_bf16 v[14:17], v[118:121], v[210:213], v[14:17]
	v_mfma_f32_16x16x32_bf16 v[10:13], v[126:129], v[210:213], v[10:13]
	v_mfma_f32_16x16x32_bf16 v[54:57], v[158:161], v[174:177], v[54:57]
	v_mfma_f32_16x16x32_bf16 v[50:53], v[166:169], v[174:177], v[50:53]
	v_mfma_f32_16x16x32_bf16 v[38:41], v[158:161], v[182:185], v[38:41]
	v_mfma_f32_16x16x32_bf16 v[34:37], v[166:169], v[182:185], v[34:37]
	v_mfma_f32_16x16x32_bf16 v[22:25], v[158:161], v[190:193], v[22:25]
	v_mfma_f32_16x16x32_bf16 v[18:21], v[166:169], v[190:193], v[18:21]
	v_mfma_f32_16x16x32_bf16 v[6:9], v[158:161], v[206:209], v[6:9]
	v_mfma_f32_16x16x32_bf16 v[2:5], v[166:169], v[206:209], v[2:5]
	v_mfma_f32_16x16x32_bf16 v[54:57], v[162:165], v[178:181], v[54:57]
	v_mfma_f32_16x16x32_bf16 v[50:53], v[170:173], v[178:181], v[50:53]
	v_mfma_f32_16x16x32_bf16 v[38:41], v[162:165], v[186:189], v[38:41]
	v_mfma_f32_16x16x32_bf16 v[34:37], v[170:173], v[186:189], v[34:37]
	v_mfma_f32_16x16x32_bf16 v[22:25], v[162:165], v[202:205], v[22:25]
	v_mfma_f32_16x16x32_bf16 v[18:21], v[170:173], v[202:205], v[18:21]
	v_mfma_f32_16x16x32_bf16 v[6:9], v[162:165], v[210:213], v[6:9]
	v_mfma_f32_16x16x32_bf16 v[2:5], v[170:173], v[210:213], v[2:5]
	s_barrier
	s_setprio 0
	s_add_i32 s65, s65, 2
	s_add_u32 s28, s28, 0x100
	s_addc_u32 s29, s29, 0
	s_add_u32 s63, s63, 0x100
	s_addc_u32 s64, s64, 0
	s_cmp_gt_u32 s65, 29
	s_cbranch_scc0 .LBB0_1272
	s_and_b64 vcc, exec, s[18:19]
	s_cbranch_vccz .LBB0_1275
	s_barrier

.LBB0_1346:
	s_or_b32 s20, s30, 1
	s_mul_hi_u32 s31, s20, 0x280000
	s_mul_i32 s42, s20, 0x280000
	s_add_u32 s20, s56, s18
	s_addc_u32 s21, s57, s19
	s_add_u32 s18, s16, 0x280000
	s_addc_u32 s19, s17, 0
	s_add_i32 s44, 0, 0x10000
	s_add_i32 s45, 0, 0x14000
	v_add_u32_e32 v146, s44, v44
	v_add_u32_e32 v162, s45, v44
	ds_read_b128 v[46:49], v146
	ds_read_b128 v[58:61], v146 offset:1024
	ds_read_b128 v[62:65], v146 offset:2048
	ds_read_b128 v[146:149], v146 offset:3072
	ds_read_b128 v[150:153], v162
	ds_read_b128 v[154:157], v162 offset:1024
	ds_read_b128 v[158:161], v162 offset:2048
	ds_read_b128 v[162:165], v162 offset:3072
	s_add_u32 s42, s62, s42
	s_addc_u32 s43, s63, s31
	v_lshl_add_u64 v[206:207], s[42:43], 0, v[194:195]
	s_add_i32 m0, s24, 0xc000
	ds_read_b128 v[166:169], v45
	ds_read_b128 v[170:173], v45 offset:1024
	ds_read_b128 v[174:177], v45 offset:2048
	ds_read_b128 v[178:181], v45 offset:3072
	ds_read_b128 v[182:185], v45 offset:4096
	ds_read_b128 v[186:189], v45 offset:5120
	ds_read_b128 v[190:193], v45 offset:6144
	ds_read_b128 v[202:205], v45 offset:7168
	global_load_lds_dwordx4 v[206:207], off
	v_lshl_add_u64 v[206:207], s[42:43], 0, v[42:43]
	s_add_i32 m0, s24, 0xe000
	s_nop 0
	global_load_lds_dwordx4 v[206:207], off
	s_waitcnt vmcnt(8)
	s_waitcnt lgkmcnt(0)
	s_setprio 1
	s_barrier
	v_mfma_f32_16x16x32_bf16 v[142:145], v[46:49], v[166:169], v[142:145]
	v_mfma_f32_16x16x32_bf16 v[138:141], v[62:65], v[166:169], v[138:141]
	v_mfma_f32_16x16x32_bf16 v[126:129], v[46:49], v[174:177], v[126:129]
	v_mfma_f32_16x16x32_bf16 v[122:125], v[62:65], v[174:177], v[122:125]
	v_mfma_f32_16x16x32_bf16 v[110:113], v[46:49], v[182:185], v[110:113]
	v_mfma_f32_16x16x32_bf16 v[106:109], v[62:65], v[182:185], v[106:109]
	v_mfma_f32_16x16x32_bf16 v[94:97], v[46:49], v[190:193], v[94:97]
	v_mfma_f32_16x16x32_bf16 v[90:93], v[62:65], v[190:193], v[90:93]
	v_mfma_f32_16x16x32_bf16 v[142:145], v[58:61], v[170:173], v[142:145]
	v_mfma_f32_16x16x32_bf16 v[138:141], v[146:149], v[170:173], v[138:141]
	v_mfma_f32_16x16x32_bf16 v[126:129], v[58:61], v[178:181], v[126:129]
	v_mfma_f32_16x16x32_bf16 v[122:125], v[146:149], v[178:181], v[122:125]
	v_mfma_f32_16x16x32_bf16 v[110:113], v[58:61], v[186:189], v[110:113]
	v_mfma_f32_16x16x32_bf16 v[106:109], v[146:149], v[186:189], v[106:109]
	v_mfma_f32_16x16x32_bf16 v[94:97], v[58:61], v[202:205], v[94:97]
	v_mfma_f32_16x16x32_bf16 v[90:93], v[146:149], v[202:205], v[90:93]
	v_mfma_f32_16x16x32_bf16 v[134:137], v[150:153], v[166:169], v[134:137]
	v_mfma_f32_16x16x32_bf16 v[130:133], v[158:161], v[166:169], v[130:133]
	v_mfma_f32_16x16x32_bf16 v[118:121], v[150:153], v[174:177], v[118:121]
	v_mfma_f32_16x16x32_bf16 v[114:117], v[158:161], v[174:177], v[114:117]
	v_mfma_f32_16x16x32_bf16 v[102:105], v[150:153], v[182:185], v[102:105]
	v_mfma_f32_16x16x32_bf16 v[98:101], v[158:161], v[182:185], v[98:101]
	v_mfma_f32_16x16x32_bf16 v[86:89], v[150:153], v[190:193], v[86:89]
	v_mfma_f32_16x16x32_bf16 v[82:85], v[158:161], v[190:193], v[82:85]
	v_mfma_f32_16x16x32_bf16 v[134:137], v[154:157], v[170:173], v[134:137]
	v_mfma_f32_16x16x32_bf16 v[130:133], v[162:165], v[170:173], v[130:133]
	v_mfma_f32_16x16x32_bf16 v[118:121], v[154:157], v[178:181], v[118:121]
	v_mfma_f32_16x16x32_bf16 v[114:117], v[162:165], v[178:181], v[114:117]
	v_mfma_f32_16x16x32_bf16 v[102:105], v[154:157], v[186:189], v[102:105]
	v_mfma_f32_16x16x32_bf16 v[98:101], v[162:165], v[186:189], v[98:101]
	v_mfma_f32_16x16x32_bf16 v[86:89], v[154:157], v[202:205], v[86:89]
	v_mfma_f32_16x16x32_bf16 v[82:85], v[162:165], v[202:205], v[82:85]
	s_barrier
	s_setprio 0
	s_add_i32 s31, s44, s23
	v_lshl_add_u64 v[206:207], s[20:21], 0, v[194:195]
	s_mov_b32 m0, s31
	ds_read_b128 v[166:169], v45 offset:16384
	ds_read_b128 v[170:173], v45 offset:17408
	ds_read_b128 v[174:177], v45 offset:18432
	ds_read_b128 v[178:181], v45 offset:19456
	ds_read_b128 v[182:185], v45 offset:20480
	ds_read_b128 v[186:189], v45 offset:21504
	ds_read_b128 v[190:193], v45 offset:22528
	ds_read_b128 v[202:205], v45 offset:23552
	global_load_lds_dwordx4 v[206:207], off
	s_add_i32 m0, s31, 0x2000
	s_add_u32 s42, s20, 0x4000
	v_lshl_add_u64 v[206:207], s[20:21], 0, v[42:43]
	s_addc_u32 s43, s21, 0
	s_add_i32 s31, s45, s23
	global_load_lds_dwordx4 v[206:207], off
	v_lshl_add_u64 v[206:207], s[42:43], 0, v[194:195]
	s_mov_b32 m0, s31
	s_nop 0
	global_load_lds_dwordx4 v[206:207], off
	v_lshl_add_u64 v[206:207], s[42:43], 0, v[42:43]
	s_add_i32 m0, s31, 0x2000
	s_nop 0
	global_load_lds_dwordx4 v[206:207], off
	v_lshl_add_u64 v[206:207], s[16:17], 0, v[194:195]
	s_mov_b32 m0, s24
	s_nop 0
	global_load_lds_dwordx4 v[206:207], off
	v_lshl_add_u64 v[206:207], s[16:17], 0, v[42:43]
	s_mov_b32 m0, s25
	s_nop 0
	global_load_lds_dwordx4 v[206:207], off
	s_waitcnt vmcnt(8)
	s_waitcnt lgkmcnt(0)
	s_setprio 1
	s_barrier
	v_mfma_f32_16x16x32_bf16 v[78:81], v[46:49], v[166:169], v[78:81]
	v_mfma_f32_16x16x32_bf16 v[74:77], v[62:65], v[166:169], v[74:77]
	v_mfma_f32_16x16x32_bf16 v[54:57], v[46:49], v[174:177], v[54:57]
	v_mfma_f32_16x16x32_bf16 v[50:53], v[62:65], v[174:177], v[50:53]
	v_mfma_f32_16x16x32_bf16 v[30:33], v[46:49], v[182:185], v[30:33]
	v_mfma_f32_16x16x32_bf16 v[26:29], v[62:65], v[182:185], v[26:29]
	v_mfma_f32_16x16x32_bf16 v[14:17], v[46:49], v[190:193], v[14:17]
	v_mfma_f32_16x16x32_bf16 v[10:13], v[62:65], v[190:193], v[10:13]
	v_mfma_f32_16x16x32_bf16 v[78:81], v[58:61], v[170:173], v[78:81]
	v_mfma_f32_16x16x32_bf16 v[74:77], v[146:149], v[170:173], v[74:77]
	v_mfma_f32_16x16x32_bf16 v[54:57], v[58:61], v[178:181], v[54:57]
	v_mfma_f32_16x16x32_bf16 v[50:53], v[146:149], v[178:181], v[50:53]
	v_mfma_f32_16x16x32_bf16 v[30:33], v[58:61], v[186:189], v[30:33]
	v_mfma_f32_16x16x32_bf16 v[26:29], v[146:149], v[186:189], v[26:29]
	v_mfma_f32_16x16x32_bf16 v[14:17], v[58:61], v[202:205], v[14:17]
	v_mfma_f32_16x16x32_bf16 v[10:13], v[146:149], v[202:205], v[10:13]
	v_mfma_f32_16x16x32_bf16 v[38:41], v[150:153], v[174:177], v[38:41]
	v_mfma_f32_16x16x32_bf16 v[34:37], v[158:161], v[174:177], v[34:37]
	v_mfma_f32_16x16x32_bf16 v[22:25], v[150:153], v[182:185], v[22:25]
	v_mfma_f32_16x16x32_bf16 v[18:21], v[158:161], v[182:185], v[18:21]
	v_mfma_f32_16x16x32_bf16 v[6:9], v[150:153], v[190:193], v[6:9]
	v_mfma_f32_16x16x32_bf16 v[2:5], v[158:161], v[190:193], v[2:5]
	v_mfma_f32_16x16x32_bf16 v[46:49], v[150:153], v[166:169], v[70:73]
	v_mfma_f32_16x16x32_bf16 v[58:61], v[158:161], v[166:169], v[66:69]
	v_mfma_f32_16x16x32_bf16 v[38:41], v[154:157], v[178:181], v[38:41]
	v_mfma_f32_16x16x32_bf16 v[34:37], v[162:165], v[178:181], v[34:37]
	v_mfma_f32_16x16x32_bf16 v[22:25], v[154:157], v[186:189], v[22:25]
	v_mfma_f32_16x16x32_bf16 v[18:21], v[162:165], v[186:189], v[18:21]
	v_mfma_f32_16x16x32_bf16 v[6:9], v[154:157], v[202:205], v[6:9]
	v_mfma_f32_16x16x32_bf16 v[2:5], v[162:165], v[202:205], v[2:5]
	v_mfma_f32_16x16x32_bf16 v[46:49], v[154:157], v[170:173], v[46:49]
	v_mfma_f32_16x16x32_bf16 v[58:61], v[162:165], v[170:173], v[58:61]
	s_barrier
	s_setprio 0
	s_add_i32 s31, 0, 0x18000
	s_add_i32 s42, 0, 0x1c000
	v_add_u32_e32 v146, s31, v44
	v_add_u32_e32 v162, s42, v44
	ds_read_b128 v[62:65], v146
	ds_read_b128 v[66:69], v146 offset:1024
	ds_read_b128 v[70:73], v146 offset:2048
	ds_read_b128 v[146:149], v146 offset:3072
	ds_read_b128 v[150:153], v162
	ds_read_b128 v[154:157], v162 offset:1024
	ds_read_b128 v[158:161], v162 offset:2048
	ds_read_b128 v[162:165], v162 offset:3072
	s_add_u32 s16, s16, 0x4000
	s_addc_u32 s17, s17, 0
	s_mov_b32 m0, s26
	v_lshl_add_u64 v[206:207], s[16:17], 0, v[194:195]
	ds_read_b128 v[166:169], v45 offset:32768
	ds_read_b128 v[170:173], v45 offset:33792
	ds_read_b128 v[174:177], v45 offset:34816
	ds_read_b128 v[178:181], v45 offset:35840
	ds_read_b128 v[182:185], v45 offset:36864
	ds_read_b128 v[186:189], v45 offset:37888
	ds_read_b128 v[190:193], v45 offset:38912
	ds_read_b128 v[202:205], v45 offset:39936
	global_load_lds_dwordx4 v[206:207], off
	v_lshl_add_u64 v[206:207], s[16:17], 0, v[42:43]
	s_mov_b32 m0, s27
	s_nop 0
	global_load_lds_dwordx4 v[206:207], off
	s_waitcnt vmcnt(8)
	s_waitcnt lgkmcnt(0)
	s_setprio 1
	s_barrier
	v_mfma_f32_16x16x32_bf16 v[142:145], v[62:65], v[166:169], v[142:145]
	v_mfma_f32_16x16x32_bf16 v[138:141], v[70:73], v[166:169], v[138:141]
	v_mfma_f32_16x16x32_bf16 v[126:129], v[62:65], v[174:177], v[126:129]
	v_mfma_f32_16x16x32_bf16 v[122:125], v[70:73], v[174:177], v[122:125]
	v_mfma_f32_16x16x32_bf16 v[110:113], v[62:65], v[182:185], v[110:113]
	v_mfma_f32_16x16x32_bf16 v[106:109], v[70:73], v[182:185], v[106:109]
	v_mfma_f32_16x16x32_bf16 v[94:97], v[62:65], v[190:193], v[94:97]
	v_mfma_f32_16x16x32_bf16 v[90:93], v[70:73], v[190:193], v[90:93]
	v_mfma_f32_16x16x32_bf16 v[142:145], v[66:69], v[170:173], v[142:145]
	v_mfma_f32_16x16x32_bf16 v[138:141], v[146:149], v[170:173], v[138:141]
	v_mfma_f32_16x16x32_bf16 v[126:129], v[66:69], v[178:181], v[126:129]
	v_mfma_f32_16x16x32_bf16 v[122:125], v[146:149], v[178:181], v[122:125]
	v_mfma_f32_16x16x32_bf16 v[110:113], v[66:69], v[186:189], v[110:113]
	v_mfma_f32_16x16x32_bf16 v[106:109], v[146:149], v[186:189], v[106:109]
	v_mfma_f32_16x16x32_bf16 v[94:97], v[66:69], v[202:205], v[94:97]
	v_mfma_f32_16x16x32_bf16 v[90:93], v[146:149], v[202:205], v[90:93]
	v_mfma_f32_16x16x32_bf16 v[134:137], v[150:153], v[166:169], v[134:137]
	v_mfma_f32_16x16x32_bf16 v[130:133], v[158:161], v[166:169], v[130:133]
	v_mfma_f32_16x16x32_bf16 v[118:121], v[150:153], v[174:177], v[118:121]
	v_mfma_f32_16x16x32_bf16 v[114:117], v[158:161], v[174:177], v[114:117]
	v_mfma_f32_16x16x32_bf16 v[102:105], v[150:153], v[182:185], v[102:105]
	v_mfma_f32_16x16x32_bf16 v[98:101], v[158:161], v[182:185], v[98:101]
	v_mfma_f32_16x16x32_bf16 v[86:89], v[150:153], v[190:193], v[86:89]
	v_mfma_f32_16x16x32_bf16 v[82:85], v[158:161], v[190:193], v[82:85]
	v_mfma_f32_16x16x32_bf16 v[134:137], v[154:157], v[170:173], v[134:137]
	v_mfma_f32_16x16x32_bf16 v[130:133], v[162:165], v[170:173], v[130:133]
	v_mfma_f32_16x16x32_bf16 v[118:121], v[154:157], v[178:181], v[118:121]
	v_mfma_f32_16x16x32_bf16 v[114:117], v[162:165], v[178:181], v[114:117]
	v_mfma_f32_16x16x32_bf16 v[102:105], v[154:157], v[186:189], v[102:105]
	v_mfma_f32_16x16x32_bf16 v[98:101], v[162:165], v[186:189], v[98:101]
	v_mfma_f32_16x16x32_bf16 v[86:89], v[154:157], v[202:205], v[86:89]
	v_mfma_f32_16x16x32_bf16 v[82:85], v[162:165], v[202:205], v[82:85]
	s_barrier
	s_setprio 0
	s_add_u32 s16, s20, 0x40000
	s_addc_u32 s17, s21, 0
	s_add_i32 s31, s31, s23
	v_lshl_add_u64 v[206:207], s[16:17], 0, v[194:195]
	s_mov_b32 m0, s31
	ds_read_b128 v[166:169], v45 offset:49152
	ds_read_b128 v[170:173], v45 offset:50176
	ds_read_b128 v[174:177], v45 offset:51200
	ds_read_b128 v[178:181], v45 offset:52224
	ds_read_b128 v[182:185], v45 offset:53248
	ds_read_b128 v[186:189], v45 offset:54272
	ds_read_b128 v[190:193], v45 offset:55296
	ds_read_b128 v[202:205], v45 offset:56320
	global_load_lds_dwordx4 v[206:207], off
	s_add_i32 m0, s31, 0x2000
	v_lshl_add_u64 v[206:207], s[16:17], 0, v[42:43]
	s_add_u32 s16, s20, 0x44000
	s_addc_u32 s17, s21, 0
	s_add_i32 s20, s42, s23
	global_load_lds_dwordx4 v[206:207], off
	v_lshl_add_u64 v[206:207], s[16:17], 0, v[194:195]
	s_mov_b32 m0, s20
	s_nop 0
	global_load_lds_dwordx4 v[206:207], off
	v_lshl_add_u64 v[206:207], s[16:17], 0, v[42:43]
	s_add_i32 m0, s20, 0x2000
	s_nop 0
	global_load_lds_dwordx4 v[206:207], off
	v_lshl_add_u64 v[206:207], s[18:19], 0, v[194:195]
	s_mov_b32 m0, s28
	s_nop 0
	global_load_lds_dwordx4 v[206:207], off
	v_lshl_add_u64 v[206:207], s[18:19], 0, v[42:43]
	s_mov_b32 m0, s29
	s_nop 0
	global_load_lds_dwordx4 v[206:207], off
	s_waitcnt vmcnt(8)
	s_waitcnt lgkmcnt(0)
	s_setprio 1
	s_barrier
	v_mfma_f32_16x16x32_bf16 v[78:81], v[62:65], v[166:169], v[78:81]
	v_mfma_f32_16x16x32_bf16 v[74:77], v[70:73], v[166:169], v[74:77]
	v_mfma_f32_16x16x32_bf16 v[54:57], v[62:65], v[174:177], v[54:57]
	v_mfma_f32_16x16x32_bf16 v[50:53], v[70:73], v[174:177], v[50:53]
	v_mfma_f32_16x16x32_bf16 v[30:33], v[62:65], v[182:185], v[30:33]
	v_mfma_f32_16x16x32_bf16 v[26:29], v[70:73], v[182:185], v[26:29]
	v_mfma_f32_16x16x32_bf16 v[14:17], v[62:65], v[190:193], v[14:17]
	v_mfma_f32_16x16x32_bf16 v[10:13], v[70:73], v[190:193], v[10:13]
	v_mfma_f32_16x16x32_bf16 v[78:81], v[66:69], v[170:173], v[78:81]
	v_mfma_f32_16x16x32_bf16 v[74:77], v[146:149], v[170:173], v[74:77]
	v_mfma_f32_16x16x32_bf16 v[54:57], v[66:69], v[178:181], v[54:57]
	v_mfma_f32_16x16x32_bf16 v[50:53], v[146:149], v[178:181], v[50:53]
	v_mfma_f32_16x16x32_bf16 v[30:33], v[66:69], v[186:189], v[30:33]
	v_mfma_f32_16x16x32_bf16 v[26:29], v[146:149], v[186:189], v[26:29]
	v_mfma_f32_16x16x32_bf16 v[14:17], v[66:69], v[202:205], v[14:17]
	v_mfma_f32_16x16x32_bf16 v[10:13], v[146:149], v[202:205], v[10:13]
	v_mfma_f32_16x16x32_bf16 v[46:49], v[150:153], v[166:169], v[46:49]
	v_mfma_f32_16x16x32_bf16 v[70:73], v[154:157], v[170:173], v[46:49]
	v_mfma_f32_16x16x32_bf16 v[46:49], v[158:161], v[166:169], v[58:61]
	v_mfma_f32_16x16x32_bf16 v[38:41], v[150:153], v[174:177], v[38:41]
	v_mfma_f32_16x16x32_bf16 v[34:37], v[158:161], v[174:177], v[34:37]
	v_mfma_f32_16x16x32_bf16 v[22:25], v[150:153], v[182:185], v[22:25]
	v_mfma_f32_16x16x32_bf16 v[18:21], v[158:161], v[182:185], v[18:21]
	v_mfma_f32_16x16x32_bf16 v[6:9], v[150:153], v[190:193], v[6:9]
	v_mfma_f32_16x16x32_bf16 v[2:5], v[158:161], v[190:193], v[2:5]
	v_mfma_f32_16x16x32_bf16 v[66:69], v[162:165], v[170:173], v[46:49]
	v_mfma_f32_16x16x32_bf16 v[38:41], v[154:157], v[178:181], v[38:41]
	v_mfma_f32_16x16x32_bf16 v[34:37], v[162:165], v[178:181], v[34:37]
	v_mfma_f32_16x16x32_bf16 v[22:25], v[154:157], v[186:189], v[22:25]
	v_mfma_f32_16x16x32_bf16 v[18:21], v[162:165], v[186:189], v[18:21]
	v_mfma_f32_16x16x32_bf16 v[6:9], v[154:157], v[202:205], v[6:9]
	v_mfma_f32_16x16x32_bf16 v[2:5], v[162:165], v[202:205], v[2:5]
	s_barrier
	s_setprio 0
	s_cmp_gt_u32 s30, 61
	s_mov_b32 s30, s4
	s_cbranch_scc1 .LBB0_1349

.LBB0_1502:
	s_or_b32 s82, s81, 1
	s_add_u32 vcc_lo, s26, vcc_lo
	s_addc_u32 vcc_hi, s27, vcc_hi
	s_and_b64 s[46:47], exec, s[46:47]
	s_cselect_b32 vcc_hi, s19, vcc_hi
	s_cselect_b32 vcc_lo, s21, vcc_lo
	s_add_u32 s46, s44, 0x280000
	s_addc_u32 s47, s45, 0
	s_add_i32 s88, 0, 0x10000
	s_add_i32 s89, 0, 0x14000
	v_add_u32_e32 v62, s88, v184
	v_add_u32_e32 v160, s89, v184
	ds_read_b128 v[50:53], v62
	ds_read_b128 v[54:57], v62 offset:1024
	ds_read_b128 v[58:61], v62 offset:2048
	ds_read_b128 v[62:65], v62 offset:3072
	ds_read_b128 v[146:149], v160
	ds_read_b128 v[150:153], v160 offset:1024
	ds_read_b128 v[156:159], v160 offset:2048
	ds_read_b128 v[160:163], v160 offset:3072
	s_mul_hi_u32 s83, s82, 0x280000
	s_mul_i32 s82, s82, 0x280000
	s_add_u32 s82, s79, s82
	s_addc_u32 s83, s80, s83
	v_lshl_add_u64 v[206:207], s[82:83], 0, v[194:195]
	s_add_i32 m0, s68, 0xc000
	ds_read_b128 v[164:167], v185
	ds_read_b128 v[168:171], v185 offset:1024
	ds_read_b128 v[172:175], v185 offset:2048
	ds_read_b128 v[176:179], v185 offset:3072
	ds_read_b128 v[180:183], v185 offset:4096
	ds_read_b128 v[186:189], v185 offset:5120
	ds_read_b128 v[190:193], v185 offset:6144
	ds_read_b128 v[202:205], v185 offset:7168
	global_load_lds_dwordx4 v[206:207], off
	v_lshl_add_u64 v[206:207], s[82:83], 0, v[154:155]
	s_add_i32 m0, s68, 0xe000
	s_nop 0
	global_load_lds_dwordx4 v[206:207], off
	s_waitcnt vmcnt(8)
	s_waitcnt lgkmcnt(0)
	s_setprio 1
	s_barrier
	v_mfma_f32_16x16x32_bf16 v[142:145], v[50:53], v[164:167], v[142:145]
	v_mfma_f32_16x16x32_bf16 v[138:141], v[58:61], v[164:167], v[138:141]
	v_mfma_f32_16x16x32_bf16 v[126:129], v[50:53], v[172:175], v[126:129]
	v_mfma_f32_16x16x32_bf16 v[122:125], v[58:61], v[172:175], v[122:125]
	v_mfma_f32_16x16x32_bf16 v[110:113], v[50:53], v[180:183], v[110:113]
	v_mfma_f32_16x16x32_bf16 v[106:109], v[58:61], v[180:183], v[106:109]
	v_mfma_f32_16x16x32_bf16 v[94:97], v[50:53], v[190:193], v[94:97]
	v_mfma_f32_16x16x32_bf16 v[90:93], v[58:61], v[190:193], v[90:93]
	v_mfma_f32_16x16x32_bf16 v[142:145], v[54:57], v[168:171], v[142:145]
	v_mfma_f32_16x16x32_bf16 v[138:141], v[62:65], v[168:171], v[138:141]
	v_mfma_f32_16x16x32_bf16 v[126:129], v[54:57], v[176:179], v[126:129]
	v_mfma_f32_16x16x32_bf16 v[122:125], v[62:65], v[176:179], v[122:125]
	v_mfma_f32_16x16x32_bf16 v[110:113], v[54:57], v[186:189], v[110:113]
	v_mfma_f32_16x16x32_bf16 v[106:109], v[62:65], v[186:189], v[106:109]
	v_mfma_f32_16x16x32_bf16 v[94:97], v[54:57], v[202:205], v[94:97]
	v_mfma_f32_16x16x32_bf16 v[90:93], v[62:65], v[202:205], v[90:93]
	v_mfma_f32_16x16x32_bf16 v[134:137], v[146:149], v[164:167], v[134:137]
	v_mfma_f32_16x16x32_bf16 v[130:133], v[156:159], v[164:167], v[130:133]
	v_mfma_f32_16x16x32_bf16 v[118:121], v[146:149], v[172:175], v[118:121]
	v_mfma_f32_16x16x32_bf16 v[114:117], v[156:159], v[172:175], v[114:117]
	v_mfma_f32_16x16x32_bf16 v[102:105], v[146:149], v[180:183], v[102:105]
	v_mfma_f32_16x16x32_bf16 v[98:101], v[156:159], v[180:183], v[98:101]
	v_mfma_f32_16x16x32_bf16 v[86:89], v[146:149], v[190:193], v[86:89]
	v_mfma_f32_16x16x32_bf16 v[82:85], v[156:159], v[190:193], v[82:85]
	v_mfma_f32_16x16x32_bf16 v[134:137], v[150:153], v[168:171], v[134:137]
	v_mfma_f32_16x16x32_bf16 v[130:133], v[160:163], v[168:171], v[130:133]
	v_mfma_f32_16x16x32_bf16 v[118:121], v[150:153], v[176:179], v[118:121]
	v_mfma_f32_16x16x32_bf16 v[114:117], v[160:163], v[176:179], v[114:117]
	v_mfma_f32_16x16x32_bf16 v[102:105], v[150:153], v[186:189], v[102:105]
	v_mfma_f32_16x16x32_bf16 v[98:101], v[160:163], v[186:189], v[98:101]
	v_mfma_f32_16x16x32_bf16 v[86:89], v[150:153], v[202:205], v[86:89]
	v_mfma_f32_16x16x32_bf16 v[82:85], v[160:163], v[202:205], v[82:85]
	s_barrier
	s_setprio 0
	s_add_i32 s82, s88, s67
	v_lshl_add_u64 v[206:207], vcc, 0, v[194:195]
	s_mov_b32 m0, s82
	ds_read_b128 v[164:167], v185 offset:16384
	ds_read_b128 v[168:171], v185 offset:17408
	ds_read_b128 v[172:175], v185 offset:18432
	ds_read_b128 v[176:179], v185 offset:19456
	ds_read_b128 v[180:183], v185 offset:20480
	ds_read_b128 v[186:189], v185 offset:21504
	ds_read_b128 v[190:193], v185 offset:22528
	ds_read_b128 v[202:205], v185 offset:23552
	global_load_lds_dwordx4 v[206:207], off
	s_add_i32 m0, s82, 0x2000
	s_add_u32 s82, vcc_lo, 0x4000
	v_lshl_add_u64 v[206:207], vcc, 0, v[154:155]
	s_addc_u32 s83, vcc_hi, 0
	s_add_i32 s88, s89, s67
	global_load_lds_dwordx4 v[206:207], off
	v_lshl_add_u64 v[206:207], s[82:83], 0, v[194:195]
	s_mov_b32 m0, s88
	s_nop 0
	global_load_lds_dwordx4 v[206:207], off
	v_lshl_add_u64 v[206:207], s[82:83], 0, v[154:155]
	s_add_i32 m0, s88, 0x2000
	s_nop 0
	global_load_lds_dwordx4 v[206:207], off
	v_lshl_add_u64 v[206:207], s[44:45], 0, v[194:195]
	s_mov_b32 m0, s68
	s_nop 0
	global_load_lds_dwordx4 v[206:207], off
	v_lshl_add_u64 v[206:207], s[44:45], 0, v[154:155]
	s_mov_b32 m0, s69
	s_nop 0
	global_load_lds_dwordx4 v[206:207], off
	s_waitcnt vmcnt(8)
	s_waitcnt lgkmcnt(0)
	s_setprio 1
	s_barrier
	v_mfma_f32_16x16x32_bf16 v[78:81], v[50:53], v[164:167], v[78:81]
	v_mfma_f32_16x16x32_bf16 v[74:77], v[58:61], v[164:167], v[74:77]
	v_mfma_f32_16x16x32_bf16 v[46:49], v[50:53], v[172:175], v[46:49]
	v_mfma_f32_16x16x32_bf16 v[42:45], v[58:61], v[172:175], v[42:45]
	v_mfma_f32_16x16x32_bf16 v[30:33], v[50:53], v[180:183], v[30:33]
	v_mfma_f32_16x16x32_bf16 v[26:29], v[58:61], v[180:183], v[26:29]
	v_mfma_f32_16x16x32_bf16 v[14:17], v[50:53], v[190:193], v[14:17]
	v_mfma_f32_16x16x32_bf16 v[10:13], v[58:61], v[190:193], v[10:13]
	v_mfma_f32_16x16x32_bf16 v[78:81], v[54:57], v[168:171], v[78:81]
	v_mfma_f32_16x16x32_bf16 v[74:77], v[62:65], v[168:171], v[74:77]
	v_mfma_f32_16x16x32_bf16 v[46:49], v[54:57], v[176:179], v[46:49]
	v_mfma_f32_16x16x32_bf16 v[42:45], v[62:65], v[176:179], v[42:45]
	v_mfma_f32_16x16x32_bf16 v[30:33], v[54:57], v[186:189], v[30:33]
	v_mfma_f32_16x16x32_bf16 v[26:29], v[62:65], v[186:189], v[26:29]
	v_mfma_f32_16x16x32_bf16 v[14:17], v[54:57], v[202:205], v[14:17]
	v_mfma_f32_16x16x32_bf16 v[10:13], v[62:65], v[202:205], v[10:13]
	v_mfma_f32_16x16x32_bf16 v[38:41], v[146:149], v[172:175], v[38:41]
	v_mfma_f32_16x16x32_bf16 v[34:37], v[156:159], v[172:175], v[34:37]
	v_mfma_f32_16x16x32_bf16 v[22:25], v[146:149], v[180:183], v[22:25]
	v_mfma_f32_16x16x32_bf16 v[18:21], v[156:159], v[180:183], v[18:21]
	v_mfma_f32_16x16x32_bf16 v[6:9], v[146:149], v[190:193], v[6:9]
	v_mfma_f32_16x16x32_bf16 v[2:5], v[156:159], v[190:193], v[2:5]
	v_mfma_f32_16x16x32_bf16 v[50:53], v[146:149], v[164:167], v[70:73]
	v_mfma_f32_16x16x32_bf16 v[54:57], v[156:159], v[164:167], v[66:69]
	v_mfma_f32_16x16x32_bf16 v[38:41], v[150:153], v[176:179], v[38:41]
	v_mfma_f32_16x16x32_bf16 v[34:37], v[160:163], v[176:179], v[34:37]
	v_mfma_f32_16x16x32_bf16 v[22:25], v[150:153], v[186:189], v[22:25]
	v_mfma_f32_16x16x32_bf16 v[18:21], v[160:163], v[186:189], v[18:21]
	v_mfma_f32_16x16x32_bf16 v[6:9], v[150:153], v[202:205], v[6:9]
	v_mfma_f32_16x16x32_bf16 v[2:5], v[160:163], v[202:205], v[2:5]
	v_mfma_f32_16x16x32_bf16 v[50:53], v[150:153], v[168:171], v[50:53]
	v_mfma_f32_16x16x32_bf16 v[54:57], v[160:163], v[168:171], v[54:57]
	s_barrier
	s_setprio 0
	s_add_i32 s82, 0, 0x18000
	s_add_i32 s83, 0, 0x1c000
	v_add_u32_e32 v70, s82, v184
	v_add_u32_e32 v160, s83, v184
	ds_read_b128 v[58:61], v70
	ds_read_b128 v[62:65], v70 offset:1024
	ds_read_b128 v[66:69], v70 offset:2048
	ds_read_b128 v[70:73], v70 offset:3072
	ds_read_b128 v[146:149], v160
	ds_read_b128 v[150:153], v160 offset:1024
	ds_read_b128 v[156:159], v160 offset:2048
	ds_read_b128 v[160:163], v160 offset:3072
	s_add_u32 s44, s44, 0x4000
	s_addc_u32 s45, s45, 0
	s_mov_b32 m0, s72
	v_lshl_add_u64 v[206:207], s[44:45], 0, v[194:195]
	ds_read_b128 v[164:167], v185 offset:32768
	ds_read_b128 v[168:171], v185 offset:33792
	ds_read_b128 v[172:175], v185 offset:34816
	ds_read_b128 v[176:179], v185 offset:35840
	ds_read_b128 v[180:183], v185 offset:36864
	ds_read_b128 v[186:189], v185 offset:37888
	ds_read_b128 v[190:193], v185 offset:38912
	ds_read_b128 v[202:205], v185 offset:39936
	global_load_lds_dwordx4 v[206:207], off
	v_lshl_add_u64 v[206:207], s[44:45], 0, v[154:155]
	s_mov_b32 m0, s73
	s_nop 0
	global_load_lds_dwordx4 v[206:207], off
	s_waitcnt vmcnt(8)
	s_waitcnt lgkmcnt(0)
	s_setprio 1
	s_barrier
	v_mfma_f32_16x16x32_bf16 v[142:145], v[58:61], v[164:167], v[142:145]
	v_mfma_f32_16x16x32_bf16 v[138:141], v[66:69], v[164:167], v[138:141]
	v_mfma_f32_16x16x32_bf16 v[126:129], v[58:61], v[172:175], v[126:129]
	v_mfma_f32_16x16x32_bf16 v[122:125], v[66:69], v[172:175], v[122:125]
	v_mfma_f32_16x16x32_bf16 v[110:113], v[58:61], v[180:183], v[110:113]
	v_mfma_f32_16x16x32_bf16 v[106:109], v[66:69], v[180:183], v[106:109]
	v_mfma_f32_16x16x32_bf16 v[94:97], v[58:61], v[190:193], v[94:97]
	v_mfma_f32_16x16x32_bf16 v[90:93], v[66:69], v[190:193], v[90:93]
	v_mfma_f32_16x16x32_bf16 v[142:145], v[62:65], v[168:171], v[142:145]
	v_mfma_f32_16x16x32_bf16 v[138:141], v[70:73], v[168:171], v[138:141]
	v_mfma_f32_16x16x32_bf16 v[126:129], v[62:65], v[176:179], v[126:129]
	v_mfma_f32_16x16x32_bf16 v[122:125], v[70:73], v[176:179], v[122:125]
	v_mfma_f32_16x16x32_bf16 v[110:113], v[62:65], v[186:189], v[110:113]
	v_mfma_f32_16x16x32_bf16 v[106:109], v[70:73], v[186:189], v[106:109]
	v_mfma_f32_16x16x32_bf16 v[94:97], v[62:65], v[202:205], v[94:97]
	v_mfma_f32_16x16x32_bf16 v[90:93], v[70:73], v[202:205], v[90:93]
	v_mfma_f32_16x16x32_bf16 v[134:137], v[146:149], v[164:167], v[134:137]
	v_mfma_f32_16x16x32_bf16 v[130:133], v[156:159], v[164:167], v[130:133]
	v_mfma_f32_16x16x32_bf16 v[118:121], v[146:149], v[172:175], v[118:121]
	v_mfma_f32_16x16x32_bf16 v[114:117], v[156:159], v[172:175], v[114:117]
	v_mfma_f32_16x16x32_bf16 v[102:105], v[146:149], v[180:183], v[102:105]
	v_mfma_f32_16x16x32_bf16 v[98:101], v[156:159], v[180:183], v[98:101]
	v_mfma_f32_16x16x32_bf16 v[86:89], v[146:149], v[190:193], v[86:89]
	v_mfma_f32_16x16x32_bf16 v[82:85], v[156:159], v[190:193], v[82:85]
	v_mfma_f32_16x16x32_bf16 v[134:137], v[150:153], v[168:171], v[134:137]
	v_mfma_f32_16x16x32_bf16 v[130:133], v[160:163], v[168:171], v[130:133]
	v_mfma_f32_16x16x32_bf16 v[118:121], v[150:153], v[176:179], v[118:121]
	v_mfma_f32_16x16x32_bf16 v[114:117], v[160:163], v[176:179], v[114:117]
	v_mfma_f32_16x16x32_bf16 v[102:105], v[150:153], v[186:189], v[102:105]
	v_mfma_f32_16x16x32_bf16 v[98:101], v[160:163], v[186:189], v[98:101]
	v_mfma_f32_16x16x32_bf16 v[86:89], v[150:153], v[202:205], v[86:89]
	v_mfma_f32_16x16x32_bf16 v[82:85], v[160:163], v[202:205], v[82:85]
	s_barrier
	s_setprio 0
	s_add_u32 s44, vcc_lo, 0x40000
	s_addc_u32 s45, vcc_hi, 0
	s_add_i32 s82, s82, s67
	v_lshl_add_u64 v[206:207], s[44:45], 0, v[194:195]
	s_mov_b32 m0, s82
	ds_read_b128 v[164:167], v185 offset:49152
	ds_read_b128 v[168:171], v185 offset:50176
	ds_read_b128 v[172:175], v185 offset:51200
	ds_read_b128 v[176:179], v185 offset:52224
	ds_read_b128 v[180:183], v185 offset:53248
	ds_read_b128 v[186:189], v185 offset:54272
	ds_read_b128 v[190:193], v185 offset:55296
	ds_read_b128 v[202:205], v185 offset:56320
	global_load_lds_dwordx4 v[206:207], off
	s_add_i32 m0, s82, 0x2000
	v_lshl_add_u64 v[206:207], s[44:45], 0, v[154:155]
	s_add_u32 s44, vcc_lo, 0x44000
	s_addc_u32 s45, vcc_hi, 0
	s_add_i32 s82, s83, s67
	global_load_lds_dwordx4 v[206:207], off
	v_lshl_add_u64 v[206:207], s[44:45], 0, v[194:195]
	s_mov_b32 m0, s82
	s_nop 0
	global_load_lds_dwordx4 v[206:207], off
	v_lshl_add_u64 v[206:207], s[44:45], 0, v[154:155]
	s_add_i32 m0, s82, 0x2000
	s_nop 0
	global_load_lds_dwordx4 v[206:207], off
	v_lshl_add_u64 v[206:207], s[46:47], 0, v[194:195]
	s_mov_b32 m0, s76
	s_nop 0
	global_load_lds_dwordx4 v[206:207], off
	v_lshl_add_u64 v[206:207], s[46:47], 0, v[154:155]
	s_mov_b32 m0, s77
	s_nop 0
	global_load_lds_dwordx4 v[206:207], off
	s_waitcnt vmcnt(8)
	s_waitcnt lgkmcnt(0)
	s_setprio 1
	s_barrier
	v_mfma_f32_16x16x32_bf16 v[78:81], v[58:61], v[164:167], v[78:81]
	v_mfma_f32_16x16x32_bf16 v[74:77], v[66:69], v[164:167], v[74:77]
	v_mfma_f32_16x16x32_bf16 v[46:49], v[58:61], v[172:175], v[46:49]
	v_mfma_f32_16x16x32_bf16 v[42:45], v[66:69], v[172:175], v[42:45]
	v_mfma_f32_16x16x32_bf16 v[30:33], v[58:61], v[180:183], v[30:33]
	v_mfma_f32_16x16x32_bf16 v[26:29], v[66:69], v[180:183], v[26:29]
	v_mfma_f32_16x16x32_bf16 v[14:17], v[58:61], v[190:193], v[14:17]
	v_mfma_f32_16x16x32_bf16 v[10:13], v[66:69], v[190:193], v[10:13]
	v_mfma_f32_16x16x32_bf16 v[78:81], v[62:65], v[168:171], v[78:81]
	v_mfma_f32_16x16x32_bf16 v[74:77], v[70:73], v[168:171], v[74:77]
	v_mfma_f32_16x16x32_bf16 v[46:49], v[62:65], v[176:179], v[46:49]
	v_mfma_f32_16x16x32_bf16 v[42:45], v[70:73], v[176:179], v[42:45]
	v_mfma_f32_16x16x32_bf16 v[30:33], v[62:65], v[186:189], v[30:33]
	v_mfma_f32_16x16x32_bf16 v[26:29], v[70:73], v[186:189], v[26:29]
	v_mfma_f32_16x16x32_bf16 v[14:17], v[62:65], v[202:205], v[14:17]
	v_mfma_f32_16x16x32_bf16 v[10:13], v[70:73], v[202:205], v[10:13]
	v_mfma_f32_16x16x32_bf16 v[50:53], v[146:149], v[164:167], v[50:53]
	v_mfma_f32_16x16x32_bf16 v[70:73], v[150:153], v[168:171], v[50:53]
	v_mfma_f32_16x16x32_bf16 v[50:53], v[156:159], v[164:167], v[54:57]
	v_mfma_f32_16x16x32_bf16 v[38:41], v[146:149], v[172:175], v[38:41]
	v_mfma_f32_16x16x32_bf16 v[34:37], v[156:159], v[172:175], v[34:37]
	v_mfma_f32_16x16x32_bf16 v[22:25], v[146:149], v[180:183], v[22:25]
	v_mfma_f32_16x16x32_bf16 v[18:21], v[156:159], v[180:183], v[18:21]
	v_mfma_f32_16x16x32_bf16 v[6:9], v[146:149], v[190:193], v[6:9]
	v_mfma_f32_16x16x32_bf16 v[2:5], v[156:159], v[190:193], v[2:5]
	v_mfma_f32_16x16x32_bf16 v[66:69], v[160:163], v[168:171], v[50:53]
	v_mfma_f32_16x16x32_bf16 v[38:41], v[150:153], v[176:179], v[38:41]
	v_mfma_f32_16x16x32_bf16 v[34:37], v[160:163], v[176:179], v[34:37]
	v_mfma_f32_16x16x32_bf16 v[22:25], v[150:153], v[186:189], v[22:25]
	v_mfma_f32_16x16x32_bf16 v[18:21], v[160:163], v[186:189], v[18:21]
	v_mfma_f32_16x16x32_bf16 v[6:9], v[150:153], v[202:205], v[6:9]
	v_mfma_f32_16x16x32_bf16 v[2:5], v[160:163], v[202:205], v[2:5]
	s_barrier
	s_setprio 0
	s_cmpk_gt_u32 s81, 0x7d
	s_mov_b32 s81, s4
	s_cbranch_scc1 .LBB0_1505
